# fused norm/residual epilogue: hb residual loads software-pipelined two groups ahead (counted vmcnt), gain vector staged in LDS
# speedup vs baseline: 1.0035x; 1.0035x over previous
; #define LAS __attribute__((address_space(3)))
;     __device__ __forceinline__ void exchange(int e, float (&sv)[2][4], float (&rv)[2][4], const Unit& u, int wr, int wc, int fr, int fq, LAS unsigned char* lds, int wid, int lane) const {
;     ...
;         if (tid < 256) {
;             const float* sl = xbuf + ((size_t)u.pm * 256 + tid) * 4;
;             const float t0 = __hip_atomic_load(sl + 0, __ATOMIC_RELAXED, __HIP_MEMORY_SCOPE_AGENT), t1 = __hip_atomic_load(sl + 1, __ATOMIC_RELAXED, __HIP_MEMORY_SCOPE_AGENT);
;             const float t2 = __hip_atomic_load(sl + 2, __ATOMIC_RELAXED, __HIP_MEMORY_SCOPE_AGENT), t3 = __hip_atomic_load(sl + 3, __ATOMIC_RELAXED, __HIP_MEMORY_SCOPE_AGENT);
;             Sx[tid] = 1.0f / sqrtf(((t0 + t1) + (t2 + t3)) * (1.0f / 1024.0f) + RMS_EPS);
;         }
;         asm volatile("s_waitcnt vmcnt(0) lgkmcnt(0)" ::: "memory"); __builtin_amdgcn_s_barrier(); asm volatile("" ::: "memory");
; #pragma unroll
;         for (int ai = 0; ai < 2; ++ai)
; #pragma unroll
;             for (int m = 0; m < 4; ++m) rv[ai][m] = Sx[ai * HALF + wr * 64 + m * 16 + fr];
;     }
;     __device__ __forceinline__ void fused(f32x4 (&acc)[2][2][4][2], const Unit& u, int wr, int wc, int fr, int fq, LAS unsigned char* lds, int wid, int lane) const {
;         bf16_t* hb = (bf16_t*)(ws + WS_HB);
;         const int row0 = u.pm * BM + wr * 64 + fr, col0 = u.pn * BM + wc * 32 + 8 * fq;
;         float sv[2][4], rv[2][4];
; #pragma unroll
;         for (int ai = 0; ai < 2; ++ai)
; #pragma unroll
;             for (int m = 0; m < 4; ++m) {
;                 float q = 0.f;
; #pragma unroll
;                 for (int bj = 0; bj < 2; ++bj)
; #pragma unroll
;                     for (int n = 0; n < 2; ++n) { const f32x4 x = acc[ai][bj][m][n]; q += (x[0] * x[0] + x[1] * x[1]) + (x[2] * x[2] + x[3] * x[3]); }
;                 sv[ai][m] = q;
;             }
;         exchange(0, sv, rv, u, wr, wc, fr, fq, lds, wid, lane);
;         float dep = 0.f;
; #pragma unroll
;         for (int ai = 0; ai < 2; ++ai)
; #pragma unroll
;             for (int m = 0; m < 4; ++m) {
;                 const bf16_t* hrow = hb + (size_t)(row0 + ai * HALF + m * 16) * DM + col0;
;                 asm volatile("" : "+v"(hrow) : "v"(dep));
;                 const float r1 = rv[ai][m];
;                 float q = 0.f;
; #pragma unroll
;                 for (int bj = 0; bj < 2; ++bj) {
.LBB0_1432:
	s_waitcnt vmcnt(0) lgkmcnt(0)
	s_barrier
	s_and_saveexec_b64 s[42:43], s[6:7]
	s_cbranch_execz .LBB0_1434
	s_lshl_b64 s[10:11], s[28:29], 12
	v_lshl_add_u64 v[146:147], v[138:139], 0, s[10:11]
	v_lshl_or_b32 v232, s26, 8, v222
	v_lshlrev_b32_e32 v232, 2, v232
	global_load_dword v233, v232, s[14:15]
	global_load_dword v148, v[146:147], off sc1
	global_load_dword v150, v[146:147], off offset:4 sc1
	global_load_dword v149, v[146:147], off offset:8 sc1
	global_load_dword v151, v[146:147], off offset:12 sc1
	s_mov_b32 s10, 0xf800000
	s_waitcnt vmcnt(0)
	v_pk_add_f32 v[146:147], v[148:149], v[150:151]
	s_nop 0
	v_add_f32_e32 v146, v146, v147
	v_fmamk_f32 v146, v146, 0x3a800000, v228
	v_mul_f32_e32 v147, 0x4f800000, v146
	v_cmp_gt_f32_e32 vcc, s10, v146
	s_nop 1
	v_cndmask_b32_e32 v146, v146, v147, vcc
	v_sqrt_f32_e32 v147, v146
	s_nop 0
	v_add_u32_e32 v148, -1, v147
	v_add_u32_e32 v149, 1, v147
	v_fma_f32 v150, -v148, v147, v146
	v_fma_f32 v151, -v149, v147, v146
	v_cmp_ge_f32_e64 s[10:11], 0, v150
	s_nop 1
	v_cndmask_b32_e64 v147, v147, v148, s[10:11]
	v_cmp_lt_f32_e64 s[10:11], 0, v151
	s_nop 1
	v_cndmask_b32_e64 v147, v147, v149, s[10:11]
	v_mul_f32_e32 v148, 0x37800000, v147
	v_cndmask_b32_e32 v147, v147, v148, vcc
	v_cmp_class_f32_e32 vcc, v146, v227
	s_nop 1
	v_cndmask_b32_e32 v146, v147, v146, vcc
	v_div_scale_f32 v147, s[10:11], v146, v146, 1.0
	v_rcp_f32_e32 v148, v147
	v_div_scale_f32 v149, vcc, 1.0, v146, 1.0
	v_fma_f32 v150, -v147, v148, 1.0
	v_fmac_f32_e32 v148, v150, v148
	v_mul_f32_e32 v150, v149, v148
	v_fma_f32 v151, -v147, v150, v149
	v_fmac_f32_e32 v150, v151, v148
	v_fma_f32 v147, -v147, v150, v149
	v_div_fmas_f32 v147, v147, v148, v150
	v_div_fixup_f32 v146, v147, v146, 1.0
	ds_write_b32 v209, v146
	v_mov_b32_e32 v234, 0x21400
	v_lshl_add_u32 v232, v222, 2, v234
	ds_write_b32 v232, v233
.LBB0_1434:
	s_or_b64 exec, exec, s[42:43]
	v_mov_b32_e32 v234, 0x21400
	v_lshl_add_u32 v231, v208, 2, v234
	v_lshl_add_u32 v146, s28, 8, v1
	v_lshl_or_b32 v156, s26, 8, v208
	v_ashrrev_i32_e32 v157, 31, v156
	v_ashrrev_i32_e32 v147, 31, v146
	v_lshl_add_u64 v[158:159], v[156:157], 1, s[22:23]
	v_lshlrev_b64 v[148:149], 11, v[146:147]
	v_lshl_add_u64 v[148:149], v[158:159], 0, v[148:149]
	s_waitcnt vmcnt(0) lgkmcnt(0)
	s_barrier
	v_mov_b64_e32 v[166:167], v[148:149]
	ds_read2_b32 v[160:161], v214 offset1:16
	ds_read2_b32 v[170:171], v214 offset0:32 offset1:48
	ds_read2_b32 v[168:169], v214 offset0:128 offset1:144
	ds_read2_b32 v[154:155], v214 offset0:160 offset1:176
	v_mov_b64_e32 v[234:235], v[148:149]
	s_mov_b32 s101, 0
	global_load_dwordx4 v[236:239], v[234:235], off
	global_load_dwordx4 v[240:243], v[234:235], off offset:256
	s_mov_b32 s100, 0x8000
	v_lshl_add_u64 v[232:233], v[234:235], 0, s[100:101]
	global_load_dwordx4 v[244:247], v[232:233], off
	global_load_dwordx4 v[248:251], v[232:233], off offset:256
	v_lshl_add_u64 v[156:157], v[156:157], 2, s[14:15]
	s_waitcnt lgkmcnt(0)
	v_pk_mul_f32 v[128:129], v[128:129], v[160:161] op_sel_hi:[1,0]
	v_pk_mul_f32 v[182:183], v[126:127], v[160:161] op_sel_hi:[1,0]
	v_pk_mul_f32 v[124:125], v[124:125], v[160:161] op_sel_hi:[1,0]
	v_pk_mul_f32 v[120:121], v[120:121], v[160:161] op_sel_hi:[1,0]
	v_pk_mul_f32 v[116:117], v[116:117], v[160:161] op_sel_hi:[1,0]
	v_mov_b32_e32 v186, v161
	v_pk_mul_f32 v[112:113], v[112:113], v[186:187] op_sel_hi:[1,0]
	v_pk_mul_f32 v[108:109], v[108:109], v[186:187] op_sel_hi:[1,0]
	v_pk_mul_f32 v[104:105], v[104:105], v[186:187] op_sel_hi:[1,0]
	v_pk_mul_f32 v[100:101], v[100:101], v[186:187] op_sel_hi:[1,0]
	v_pk_mul_f32 v[96:97], v[96:97], v[170:171] op_sel_hi:[1,0]
	v_pk_mul_f32 v[188:189], v[94:95], v[170:171] op_sel_hi:[1,0]
	v_pk_mul_f32 v[92:93], v[92:93], v[170:171] op_sel_hi:[1,0]
	v_pk_mul_f32 v[88:89], v[88:89], v[170:171] op_sel_hi:[1,0]
	v_pk_mul_f32 v[84:85], v[84:85], v[170:171] op_sel_hi:[1,0]
	v_mov_b32_e32 v192, v171
	v_pk_mul_f32 v[80:81], v[80:81], v[192:193] op_sel_hi:[1,0]
	v_pk_mul_f32 v[76:77], v[76:77], v[192:193] op_sel_hi:[1,0]
	v_pk_mul_f32 v[72:73], v[72:73], v[192:193] op_sel_hi:[1,0]
	v_pk_mul_f32 v[68:69], v[68:69], v[192:193] op_sel_hi:[1,0]
	v_pk_mul_f32 v[64:65], v[64:65], v[168:169] op_sel_hi:[1,0]
	v_pk_mul_f32 v[194:195], v[62:63], v[168:169] op_sel_hi:[1,0]
	v_pk_mul_f32 v[60:61], v[60:61], v[168:169] op_sel_hi:[1,0]
	v_pk_mul_f32 v[56:57], v[56:57], v[168:169] op_sel_hi:[1,0]
	v_pk_mul_f32 v[52:53], v[52:53], v[168:169] op_sel_hi:[1,0]
	v_mov_b32_e32 v198, v169
	v_pk_mul_f32 v[48:49], v[48:49], v[198:199] op_sel_hi:[1,0]
	v_pk_mul_f32 v[44:45], v[44:45], v[198:199] op_sel_hi:[1,0]
	v_pk_mul_f32 v[38:39], v[38:39], v[198:199] op_sel_hi:[1,0]
	v_pk_mul_f32 v[40:41], v[40:41], v[198:199] op_sel_hi:[1,0]
	v_pk_mul_f32 v[36:37], v[36:37], v[198:199] op_sel_hi:[1,0]
	v_pk_mul_f32 v[34:35], v[34:35], v[198:199] op_sel_hi:[1,0]
	v_pk_mul_f32 v[32:33], v[32:33], v[154:155] op_sel_hi:[1,0]
	v_pk_mul_f32 v[28:29], v[28:29], v[154:155] op_sel_hi:[1,0]
	v_pk_mul_f32 v[26:27], v[26:27], v[154:155] op_sel_hi:[1,0]
	v_pk_mul_f32 v[30:31], v[30:31], v[154:155] op_sel_hi:[1,0]
	v_pk_mul_f32 v[22:23], v[22:23], v[154:155] op_sel_hi:[1,0]
	v_pk_mul_f32 v[24:25], v[24:25], v[154:155] op_sel_hi:[1,0]
	v_pk_mul_f32 v[20:21], v[20:21], v[154:155] op_sel_hi:[1,0]
	v_pk_mul_f32 v[18:19], v[18:19], v[154:155] op_sel_hi:[1,0]
	v_add_u32_e32 v206, 0xb0, v146
	v_ashrrev_i32_e32 v207, 31, v206
	s_waitcnt vmcnt(2)
;     __device__ __forceinline__ void fused(f32x4 (&acc)[2][2][4][2], const Unit& u, int wr, int wc, int fr, int fq, LAS unsigned char* lds, int wid, int lane) const {
;     ...
; #pragma unroll
;             for (int m = 0; m < 4; ++m) {
;                 const bf16_t* hrow = hb + (size_t)(row0 + ai * HALF + m * 16) * DM + col0;
;                 asm volatile("" : "+v"(hrow) : "v"(dep));
;                 const float r1 = rv[ai][m];
;                 float q = 0.f;
; #pragma unroll
;                 for (int bj = 0; bj < 2; ++bj) {
;                     const u32x4 hv = *(const u32x4*)(hrow + bj * HALF);
;                     const f32x4 h0 = (f32x4){__uint_as_float(hv.x << 16), __uint_as_float(hv.x & 0xffff0000u), __uint_as_float(hv.y << 16), __uint_as_float(hv.y & 0xffff0000u)};
;                     const f32x4 h1 = (f32x4){__uint_as_float(hv.z << 16), __uint_as_float(hv.z & 0xffff0000u), __uint_as_float(hv.w << 16), __uint_as_float(hv.w & 0xffff0000u)};
;                     const f32x4 gg0 = *(const f32x4*)(gpost + col0 + bj * HALF), gg1 = *(const f32x4*)(gpost + col0 + bj * HALF + 4);
;                     f32x4 x0 = h0 + acc[ai][bj][m][0] * r1 * gg0, x1 = h1 + acc[ai][bj][m][1] * r1 * gg1;
;                     acc[ai][bj][m][0] = x0; acc[ai][bj][m][1] = x1;
;                     q += ((x0[0] * x0[0] + x0[1] * x0[1]) + (x0[2] * x0[2] + x0[3] * x0[3])) + ((x1[0] * x1[0] + x1[1] * x1[1]) + (x1[2] * x1[2] + x1[3] * x1[3]));
	ds_read_b128 v[150:153], v231 offset:16
	ds_read_b128 v[162:165], v231 offset:0
	v_lshlrev_b32_e32 v172, 16, v236
	v_and_b32_e32 v173, 0xffff0000, v236
	v_lshlrev_b32_e32 v174, 16, v237
	v_and_b32_e32 v175, 0xffff0000, v237
	v_lshlrev_b32_e32 v176, 16, v238
	v_and_b32_e32 v177, 0xffff0000, v238
	v_lshlrev_b32_e32 v178, 16, v239
	v_and_b32_e32 v179, 0xffff0000, v239
	s_mov_b32 s100, 0x10000
	v_lshl_add_u64 v[232:233], v[234:235], 0, s[100:101]
	global_load_dwordx4 v[236:239], v[232:233], off
	s_waitcnt lgkmcnt(0)
	v_pk_fma_f32 v[126:127], v[128:129], v[164:165], v[174:175]
	v_pk_fma_f32 v[128:129], v[182:183], v[162:163], v[172:173]
	v_pk_mul_f32 v[162:163], v[122:123], v[160:161] op_sel_hi:[1,0]
	v_pk_fma_f32 v[122:123], v[124:125], v[152:153], v[178:179]
	v_pk_fma_f32 v[124:125], v[162:163], v[150:151], v[176:177]
	ds_read_b128 v[150:153], v231 offset:528
	ds_read_b128 v[162:165], v231 offset:512
	v_pk_mul_f32 v[178:179], v[118:119], v[160:161] op_sel_hi:[1,0]
	s_waitcnt lgkmcnt(0)
	v_lshlrev_b32_e32 v166, 16, v240
	v_and_b32_e32 v167, 0xffff0000, v240
	v_lshlrev_b32_e32 v172, 16, v241
	v_and_b32_e32 v173, 0xffff0000, v241
	v_lshlrev_b32_e32 v174, 16, v242
	v_and_b32_e32 v175, 0xffff0000, v242
	v_lshlrev_b32_e32 v176, 16, v243
	v_and_b32_e32 v177, 0xffff0000, v243
	global_load_dwordx4 v[240:243], v[232:233], off offset:256
	s_waitcnt lgkmcnt(0)
	v_pk_fma_f32 v[118:119], v[120:121], v[164:165], v[172:173]
	v_pk_fma_f32 v[120:121], v[178:179], v[162:163], v[166:167]
	v_pk_mul_f32 v[162:163], v[114:115], v[160:161] op_sel_hi:[1,0]
	v_pk_fma_f32 v[114:115], v[116:117], v[152:153], v[176:177]
	v_mov_b32_e32 v152, v129
	v_mov_b32_e32 v153, v121
	v_pk_fma_f32 v[116:117], v[162:163], v[150:151], v[174:175]
	v_mov_b32_e32 v150, v128
	v_mov_b32_e32 v151, v120
	v_pk_mul_f32 v[152:153], v[152:153], v[152:153]
	v_mov_b32_e32 v162, v127
	v_mov_b32_e32 v163, v119
	v_pk_fma_f32 v[150:151], v[150:151], v[150:151], v[152:153]
	v_mov_b32_e32 v152, v126
	v_mov_b32_e32 v153, v118
	v_pk_mul_f32 v[162:163], v[162:163], v[162:163]
	v_mov_b32_e32 v164, v123
	v_pk_fma_f32 v[152:153], v[152:153], v[152:153], v[162:163]
	v_mov_b32_e32 v162, v125
	v_mov_b32_e32 v163, v117
	v_pk_add_f32 v[150:151], v[150:151], v[152:153]
	v_mov_b32_e32 v152, v124
	v_mov_b32_e32 v153, v116
	v_pk_mul_f32 v[162:163], v[162:163], v[162:163]
	v_mov_b32_e32 v165, v115
	v_pk_fma_f32 v[152:153], v[152:153], v[152:153], v[162:163]
	v_mov_b32_e32 v162, v122
	v_mov_b32_e32 v163, v114
	v_pk_mul_f32 v[164:165], v[164:165], v[164:165]
	v_pk_mul_f32 v[160:161], v[110:111], v[186:187] op_sel_hi:[1,0]
	v_pk_fma_f32 v[162:163], v[162:163], v[162:163], v[164:165]
	s_nop 0
	v_pk_add_f32 v[152:153], v[152:153], v[162:163]
	s_nop 0
	v_pk_add_f32 v[150:151], v[150:151], v[152:153]
	s_nop 0
	v_add_f32_e32 v216, v150, v151
	v_or_b32_e32 v150, 16, v146
	v_ashrrev_i32_e32 v151, 31, v150
	v_lshlrev_b64 v[152:153], 11, v[150:151]
	v_lshl_add_u64 v[152:153], v[158:159], 0, v[152:153]
	v_mov_b64_e32 v[162:163], v[152:153]
	s_waitcnt vmcnt(2)
	ds_read_b128 v[164:167], v231 offset:16
	ds_read_b128 v[172:175], v231 offset:0
	v_lshlrev_b32_e32 v176, 16, v244
	v_and_b32_e32 v177, 0xffff0000, v244
	v_lshlrev_b32_e32 v178, 16, v245
	v_and_b32_e32 v179, 0xffff0000, v245
	v_lshlrev_b32_e32 v182, 16, v246
	v_and_b32_e32 v183, 0xffff0000, v246
	v_lshlrev_b32_e32 v184, 16, v247
	v_and_b32_e32 v185, 0xffff0000, v247
	s_mov_b32 s100, 0x18000
	v_lshl_add_u64 v[232:233], v[234:235], 0, s[100:101]
	global_load_dwordx4 v[244:247], v[232:233], off
	s_waitcnt lgkmcnt(0)
	v_pk_fma_f32 v[110:111], v[112:113], v[174:175], v[178:179]
	v_pk_fma_f32 v[112:113], v[160:161], v[172:173], v[176:177]
	v_pk_mul_f32 v[160:161], v[106:107], v[186:187] op_sel_hi:[1,0]
	v_pk_fma_f32 v[106:107], v[108:109], v[166:167], v[184:185]
	v_pk_fma_f32 v[108:109], v[160:161], v[164:165], v[182:183]
	ds_read_b128 v[160:163], v231 offset:528
	ds_read_b128 v[164:167], v231 offset:512
	v_pk_mul_f32 v[182:183], v[102:103], v[186:187] op_sel_hi:[1,0]
	s_waitcnt lgkmcnt(0)
	v_lshlrev_b32_e32 v172, 16, v248
	v_and_b32_e32 v173, 0xffff0000, v248
	v_lshlrev_b32_e32 v174, 16, v249
	v_and_b32_e32 v175, 0xffff0000, v249
	v_lshlrev_b32_e32 v176, 16, v250
	v_and_b32_e32 v177, 0xffff0000, v250
	v_lshlrev_b32_e32 v178, 16, v251
	v_and_b32_e32 v179, 0xffff0000, v251
	global_load_dwordx4 v[248:251], v[232:233], off offset:256
	s_waitcnt lgkmcnt(0)
	v_pk_fma_f32 v[102:103], v[104:105], v[166:167], v[174:175]
	v_pk_fma_f32 v[104:105], v[182:183], v[164:165], v[172:173]
	v_pk_mul_f32 v[164:165], v[98:99], v[186:187] op_sel_hi:[1,0]
	v_pk_fma_f32 v[98:99], v[100:101], v[162:163], v[178:179]
	v_mov_b32_e32 v162, v113
	v_mov_b32_e32 v163, v105
	v_pk_fma_f32 v[100:101], v[164:165], v[160:161], v[176:177]
	v_mov_b32_e32 v160, v112
	v_mov_b32_e32 v161, v104
	v_pk_mul_f32 v[162:163], v[162:163], v[162:163]
	v_mov_b32_e32 v164, v111
	v_mov_b32_e32 v165, v103
	v_pk_fma_f32 v[160:161], v[160:161], v[160:161], v[162:163]
	v_mov_b32_e32 v162, v110
	v_mov_b32_e32 v163, v102
	v_pk_mul_f32 v[164:165], v[164:165], v[164:165]
	v_mov_b32_e32 v166, v107
	v_pk_fma_f32 v[162:163], v[162:163], v[162:163], v[164:165]
	v_mov_b32_e32 v164, v109
	v_mov_b32_e32 v165, v101
	v_pk_add_f32 v[160:161], v[160:161], v[162:163]
	v_mov_b32_e32 v162, v108
	v_mov_b32_e32 v163, v100
	v_pk_mul_f32 v[164:165], v[164:165], v[164:165]
	v_mov_b32_e32 v167, v99
	v_pk_fma_f32 v[162:163], v[162:163], v[162:163], v[164:165]
	v_mov_b32_e32 v164, v106
	v_mov_b32_e32 v165, v98
	v_pk_mul_f32 v[166:167], v[166:167], v[166:167]
	s_nop 0
	v_pk_fma_f32 v[164:165], v[164:165], v[164:165], v[166:167]
	s_nop 0
	v_pk_add_f32 v[162:163], v[162:163], v[164:165]
	s_nop 0
	v_pk_add_f32 v[160:161], v[160:161], v[162:163]
	s_nop 0
	v_add_f32_e32 v217, v160, v161
	v_or_b32_e32 v160, 32, v146
	v_ashrrev_i32_e32 v161, 31, v160
	v_lshlrev_b64 v[162:163], 11, v[160:161]
	v_lshl_add_u64 v[162:163], v[158:159], 0, v[162:163]
	v_mov_b64_e32 v[164:165], v[162:163]
	s_waitcnt vmcnt(2)
;     __device__ __forceinline__ void fused(f32x4 (&acc)[2][2][4][2], const Unit& u, int wr, int wc, int fr, int fq, LAS unsigned char* lds, int wid, int lane) const {
;     ...
;         float dep = 0.f;
; #pragma unroll
;         for (int ai = 0; ai < 2; ++ai)
; #pragma unroll
;             for (int m = 0; m < 4; ++m) {
;                 const bf16_t* hrow = hb + (size_t)(row0 + ai * HALF + m * 16) * DM + col0;
;                 asm volatile("" : "+v"(hrow) : "v"(dep));
;                 const float r1 = rv[ai][m];
;                 float q = 0.f;
; #pragma unroll
;                 for (int bj = 0; bj < 2; ++bj) {
;                     const u32x4 hv = *(const u32x4*)(hrow + bj * HALF);
;                     const f32x4 h0 = (f32x4){__uint_as_float(hv.x << 16), __uint_as_float(hv.x & 0xffff0000u), __uint_as_float(hv.y << 16), __uint_as_float(hv.y & 0xffff0000u)};
;                     const f32x4 h1 = (f32x4){__uint_as_float(hv.z << 16), __uint_as_float(hv.z & 0xffff0000u), __uint_as_float(hv.w << 16), __uint_as_float(hv.w & 0xffff0000u)};
;                     const f32x4 gg0 = *(const f32x4*)(gpost + col0 + bj * HALF), gg1 = *(const f32x4*)(gpost + col0 + bj * HALF + 4);
;                     f32x4 x0 = h0 + acc[ai][bj][m][0] * r1 * gg0, x1 = h1 + acc[ai][bj][m][1] * r1 * gg1;
;                     acc[ai][bj][m][0] = x0; acc[ai][bj][m][1] = x1;
;                     q += ((x0[0] * x0[0] + x0[1] * x0[1]) + (x0[2] * x0[2] + x0[3] * x0[3])) + ((x1[0] * x1[0] + x1[1] * x1[1]) + (x1[2] * x1[2] + x1[3] * x1[3]));
;                 }
;                 sv[ai][m] = q;
;                 dep = q;
;             }
	ds_read_b128 v[172:175], v231 offset:16
	ds_read_b128 v[176:179], v231 offset:0
	v_lshlrev_b32_e32 v166, 16, v236
	v_and_b32_e32 v167, 0xffff0000, v236
	v_lshlrev_b32_e32 v182, 16, v237
	v_and_b32_e32 v183, 0xffff0000, v237
	v_lshlrev_b32_e32 v184, 16, v238
	v_and_b32_e32 v185, 0xffff0000, v238
	v_lshlrev_b32_e32 v186, 16, v239
	v_and_b32_e32 v187, 0xffff0000, v239
	s_mov_b32 s100, 0x40000
	v_lshl_add_u64 v[232:233], v[234:235], 0, s[100:101]
	global_load_dwordx4 v[236:239], v[232:233], off
	s_waitcnt lgkmcnt(0)
	v_pk_fma_f32 v[94:95], v[96:97], v[178:179], v[182:183]
	v_pk_fma_f32 v[96:97], v[188:189], v[176:177], v[166:167]
	v_pk_mul_f32 v[166:167], v[90:91], v[170:171] op_sel_hi:[1,0]
	v_pk_fma_f32 v[90:91], v[92:93], v[174:175], v[186:187]
	v_pk_fma_f32 v[92:93], v[166:167], v[172:173], v[184:185]
	ds_read_b128 v[164:167], v231 offset:528
	ds_read_b128 v[172:175], v231 offset:512
	v_pk_mul_f32 v[186:187], v[86:87], v[170:171] op_sel_hi:[1,0]
	s_waitcnt lgkmcnt(0)
	v_lshlrev_b32_e32 v176, 16, v240
	v_and_b32_e32 v177, 0xffff0000, v240
	v_lshlrev_b32_e32 v178, 16, v241
	v_and_b32_e32 v179, 0xffff0000, v241
	v_lshlrev_b32_e32 v182, 16, v242
	v_and_b32_e32 v183, 0xffff0000, v242
	v_lshlrev_b32_e32 v184, 16, v243
	v_and_b32_e32 v185, 0xffff0000, v243
	global_load_dwordx4 v[240:243], v[232:233], off offset:256
	s_waitcnt lgkmcnt(0)
	v_pk_fma_f32 v[86:87], v[88:89], v[174:175], v[178:179]
	v_pk_fma_f32 v[88:89], v[186:187], v[172:173], v[176:177]
	v_pk_mul_f32 v[172:173], v[82:83], v[170:171] op_sel_hi:[1,0]
	v_pk_fma_f32 v[82:83], v[84:85], v[166:167], v[184:185]
	v_mov_b32_e32 v166, v97
	v_mov_b32_e32 v167, v89
	v_pk_fma_f32 v[84:85], v[172:173], v[164:165], v[182:183]
	v_mov_b32_e32 v164, v96
	v_mov_b32_e32 v165, v88
	v_pk_mul_f32 v[166:167], v[166:167], v[166:167]
	v_mov_b32_e32 v172, v95
	v_mov_b32_e32 v173, v87
	v_pk_fma_f32 v[164:165], v[164:165], v[164:165], v[166:167]
	v_mov_b32_e32 v166, v94
	v_mov_b32_e32 v167, v86
	v_pk_mul_f32 v[172:173], v[172:173], v[172:173]
	v_mov_b32_e32 v174, v91
	v_pk_fma_f32 v[166:167], v[166:167], v[166:167], v[172:173]
	v_mov_b32_e32 v172, v93
	v_mov_b32_e32 v173, v85
	v_pk_add_f32 v[164:165], v[164:165], v[166:167]
	v_mov_b32_e32 v166, v92
	v_mov_b32_e32 v167, v84
	v_pk_mul_f32 v[172:173], v[172:173], v[172:173]
	v_mov_b32_e32 v175, v83
	v_pk_fma_f32 v[166:167], v[166:167], v[166:167], v[172:173]
	v_mov_b32_e32 v172, v90
	v_mov_b32_e32 v173, v82
	v_pk_mul_f32 v[174:175], v[174:175], v[174:175]
	v_pk_mul_f32 v[170:171], v[78:79], v[192:193] op_sel_hi:[1,0]
	v_pk_fma_f32 v[172:173], v[172:173], v[172:173], v[174:175]
	s_nop 0
	v_pk_add_f32 v[166:167], v[166:167], v[172:173]
	s_nop 0
	v_pk_add_f32 v[164:165], v[164:165], v[166:167]
	s_nop 0
	v_add_f32_e32 v218, v164, v165
	v_or_b32_e32 v164, 48, v146
	v_ashrrev_i32_e32 v165, 31, v164
	v_lshlrev_b64 v[166:167], 11, v[164:165]
	v_lshl_add_u64 v[166:167], v[158:159], 0, v[166:167]
	v_mov_b64_e32 v[172:173], v[166:167]
	s_waitcnt vmcnt(2)
	ds_read_b128 v[174:177], v231 offset:16
	ds_read_b128 v[182:185], v231 offset:0
	v_lshlrev_b32_e32 v178, 16, v244
	v_and_b32_e32 v179, 0xffff0000, v244
	v_lshlrev_b32_e32 v186, 16, v245
	v_and_b32_e32 v187, 0xffff0000, v245
	v_lshlrev_b32_e32 v188, 16, v246
	v_and_b32_e32 v189, 0xffff0000, v246
	v_lshlrev_b32_e32 v190, 16, v247
	v_and_b32_e32 v191, 0xffff0000, v247
	s_mov_b32 s100, 0x48000
	v_lshl_add_u64 v[232:233], v[234:235], 0, s[100:101]
	global_load_dwordx4 v[244:247], v[232:233], off
	s_waitcnt lgkmcnt(0)
	v_pk_fma_f32 v[78:79], v[80:81], v[184:185], v[186:187]
	v_pk_fma_f32 v[80:81], v[170:171], v[182:183], v[178:179]
	v_pk_mul_f32 v[170:171], v[74:75], v[192:193] op_sel_hi:[1,0]
	v_pk_fma_f32 v[74:75], v[76:77], v[176:177], v[190:191]
	v_pk_fma_f32 v[76:77], v[170:171], v[174:175], v[188:189]
	ds_read_b128 v[170:173], v231 offset:528
	ds_read_b128 v[174:177], v231 offset:512
	v_pk_mul_f32 v[188:189], v[70:71], v[192:193] op_sel_hi:[1,0]
	s_waitcnt lgkmcnt(0)
	v_lshlrev_b32_e32 v178, 16, v248
	v_and_b32_e32 v179, 0xffff0000, v248
	v_lshlrev_b32_e32 v182, 16, v249
	v_and_b32_e32 v183, 0xffff0000, v249
	v_lshlrev_b32_e32 v184, 16, v250
	v_and_b32_e32 v185, 0xffff0000, v250
	v_lshlrev_b32_e32 v186, 16, v251
	v_and_b32_e32 v187, 0xffff0000, v251
	global_load_dwordx4 v[248:251], v[232:233], off offset:256
	s_waitcnt lgkmcnt(0)
	v_pk_fma_f32 v[70:71], v[72:73], v[176:177], v[182:183]
	v_pk_fma_f32 v[72:73], v[188:189], v[174:175], v[178:179]
	v_pk_mul_f32 v[174:175], v[66:67], v[192:193] op_sel_hi:[1,0]
	v_pk_fma_f32 v[66:67], v[68:69], v[172:173], v[186:187]
	v_mov_b32_e32 v172, v81
	v_mov_b32_e32 v173, v73
	v_pk_fma_f32 v[68:69], v[174:175], v[170:171], v[184:185]
	v_mov_b32_e32 v170, v80
	v_mov_b32_e32 v171, v72
	v_pk_mul_f32 v[172:173], v[172:173], v[172:173]
	v_mov_b32_e32 v174, v79
	v_mov_b32_e32 v175, v71
	v_pk_fma_f32 v[170:171], v[170:171], v[170:171], v[172:173]
	v_mov_b32_e32 v172, v78
	v_mov_b32_e32 v173, v70
	v_pk_mul_f32 v[174:175], v[174:175], v[174:175]
	v_mov_b32_e32 v176, v75
	v_pk_fma_f32 v[172:173], v[172:173], v[172:173], v[174:175]
	v_mov_b32_e32 v174, v77
	v_mov_b32_e32 v175, v69
	v_pk_add_f32 v[170:171], v[170:171], v[172:173]
	v_mov_b32_e32 v172, v76
	v_mov_b32_e32 v173, v68
	v_pk_mul_f32 v[174:175], v[174:175], v[174:175]
	v_mov_b32_e32 v177, v67
	v_pk_fma_f32 v[172:173], v[172:173], v[172:173], v[174:175]
	v_mov_b32_e32 v174, v74
	v_mov_b32_e32 v175, v66
	v_pk_mul_f32 v[176:177], v[176:177], v[176:177]
	s_nop 0
	v_pk_fma_f32 v[174:175], v[174:175], v[174:175], v[176:177]
	s_nop 0
	v_pk_add_f32 v[172:173], v[172:173], v[174:175]
	s_nop 0
	v_pk_add_f32 v[170:171], v[170:171], v[172:173]
	s_nop 0
	v_add_f32_e32 v219, v170, v171
	v_add_u32_e32 v170, 0x80, v146
	v_ashrrev_i32_e32 v171, 31, v170
	v_lshlrev_b64 v[172:173], 11, v[170:171]
	v_lshl_add_u64 v[172:173], v[158:159], 0, v[172:173]
	v_mov_b64_e32 v[174:175], v[172:173]
	s_waitcnt vmcnt(2)
;     __device__ __forceinline__ void fused(f32x4 (&acc)[2][2][4][2], const Unit& u, int wr, int wc, int fr, int fq, LAS unsigned char* lds, int wid, int lane) const {
;     ...
;         float dep = 0.f;
; #pragma unroll
;         for (int ai = 0; ai < 2; ++ai)
; #pragma unroll
;             for (int m = 0; m < 4; ++m) {
;                 const bf16_t* hrow = hb + (size_t)(row0 + ai * HALF + m * 16) * DM + col0;
;                 asm volatile("" : "+v"(hrow) : "v"(dep));
;                 const float r1 = rv[ai][m];
;                 float q = 0.f;
; #pragma unroll
;                 for (int bj = 0; bj < 2; ++bj) {
;                     const u32x4 hv = *(const u32x4*)(hrow + bj * HALF);
;                     const f32x4 h0 = (f32x4){__uint_as_float(hv.x << 16), __uint_as_float(hv.x & 0xffff0000u), __uint_as_float(hv.y << 16), __uint_as_float(hv.y & 0xffff0000u)};
;                     const f32x4 h1 = (f32x4){__uint_as_float(hv.z << 16), __uint_as_float(hv.z & 0xffff0000u), __uint_as_float(hv.w << 16), __uint_as_float(hv.w & 0xffff0000u)};
;                     const f32x4 gg0 = *(const f32x4*)(gpost + col0 + bj * HALF), gg1 = *(const f32x4*)(gpost + col0 + bj * HALF + 4);
;                     f32x4 x0 = h0 + acc[ai][bj][m][0] * r1 * gg0, x1 = h1 + acc[ai][bj][m][1] * r1 * gg1;
;                     acc[ai][bj][m][0] = x0; acc[ai][bj][m][1] = x1;
;                     q += ((x0[0] * x0[0] + x0[1] * x0[1]) + (x0[2] * x0[2] + x0[3] * x0[3])) + ((x1[0] * x1[0] + x1[1] * x1[1]) + (x1[2] * x1[2] + x1[3] * x1[3]));
;                 }
;                 sv[ai][m] = q;
;                 dep = q;
;             }
	ds_read_b128 v[176:179], v231 offset:16
	ds_read_b128 v[182:185], v231 offset:0
	v_lshlrev_b32_e32 v186, 16, v236
	v_and_b32_e32 v187, 0xffff0000, v236
	v_lshlrev_b32_e32 v188, 16, v237
	v_and_b32_e32 v189, 0xffff0000, v237
	v_lshlrev_b32_e32 v190, 16, v238
	v_and_b32_e32 v191, 0xffff0000, v238
	v_lshlrev_b32_e32 v192, 16, v239
	v_and_b32_e32 v193, 0xffff0000, v239
	s_mov_b32 s100, 0x50000
	v_lshl_add_u64 v[232:233], v[234:235], 0, s[100:101]
	global_load_dwordx4 v[236:239], v[232:233], off
	s_waitcnt lgkmcnt(0)
	v_pk_fma_f32 v[62:63], v[64:65], v[184:185], v[188:189]
	v_pk_fma_f32 v[64:65], v[194:195], v[182:183], v[186:187]
	v_pk_mul_f32 v[182:183], v[58:59], v[168:169] op_sel_hi:[1,0]
	v_pk_fma_f32 v[58:59], v[60:61], v[178:179], v[192:193]
	v_pk_fma_f32 v[60:61], v[182:183], v[176:177], v[190:191]
	ds_read_b128 v[174:177], v231 offset:528
	ds_read_b128 v[182:185], v231 offset:512
	v_pk_mul_f32 v[192:193], v[54:55], v[168:169] op_sel_hi:[1,0]
	s_waitcnt lgkmcnt(0)
	v_lshlrev_b32_e32 v178, 16, v240
	v_and_b32_e32 v179, 0xffff0000, v240
	v_lshlrev_b32_e32 v186, 16, v241
	v_and_b32_e32 v187, 0xffff0000, v241
	v_lshlrev_b32_e32 v188, 16, v242
	v_and_b32_e32 v189, 0xffff0000, v242
	v_lshlrev_b32_e32 v190, 16, v243
	v_and_b32_e32 v191, 0xffff0000, v243
	global_load_dwordx4 v[240:243], v[232:233], off offset:256
	s_waitcnt lgkmcnt(0)
	v_pk_fma_f32 v[54:55], v[56:57], v[184:185], v[186:187]
	v_pk_fma_f32 v[56:57], v[192:193], v[182:183], v[178:179]
	v_pk_mul_f32 v[178:179], v[50:51], v[168:169] op_sel_hi:[1,0]
	v_pk_fma_f32 v[50:51], v[52:53], v[176:177], v[190:191]
	v_mov_b32_e32 v176, v65
	v_mov_b32_e32 v177, v57
	v_pk_fma_f32 v[52:53], v[178:179], v[174:175], v[188:189]
	v_mov_b32_e32 v174, v64
	v_mov_b32_e32 v175, v56
	v_pk_mul_f32 v[176:177], v[176:177], v[176:177]
	v_mov_b32_e32 v178, v63
	v_mov_b32_e32 v179, v55
	v_pk_fma_f32 v[174:175], v[174:175], v[174:175], v[176:177]
	v_mov_b32_e32 v176, v62
	v_mov_b32_e32 v177, v54
	v_pk_mul_f32 v[178:179], v[178:179], v[178:179]
	v_mov_b32_e32 v182, v59
	v_pk_fma_f32 v[176:177], v[176:177], v[176:177], v[178:179]
	v_mov_b32_e32 v178, v61
	v_mov_b32_e32 v179, v53
	v_pk_add_f32 v[174:175], v[174:175], v[176:177]
	v_mov_b32_e32 v176, v60
	v_mov_b32_e32 v177, v52
	v_pk_mul_f32 v[178:179], v[178:179], v[178:179]
	v_mov_b32_e32 v183, v51
	v_pk_fma_f32 v[176:177], v[176:177], v[176:177], v[178:179]
	v_mov_b32_e32 v178, v58
	v_mov_b32_e32 v179, v50
	v_pk_mul_f32 v[182:183], v[182:183], v[182:183]
	v_pk_mul_f32 v[168:169], v[46:47], v[198:199] op_sel_hi:[1,0]
	v_pk_fma_f32 v[178:179], v[178:179], v[178:179], v[182:183]
	s_nop 0
	v_pk_add_f32 v[176:177], v[176:177], v[178:179]
	s_nop 0
	v_pk_add_f32 v[174:175], v[174:175], v[176:177]
	s_nop 0
	v_add_f32_e32 v220, v174, v175
	v_add_u32_e32 v174, 0x90, v146
	v_ashrrev_i32_e32 v175, 31, v174
	v_lshlrev_b64 v[176:177], 11, v[174:175]
	v_lshl_add_u64 v[176:177], v[158:159], 0, v[176:177]
	v_mov_b64_e32 v[178:179], v[176:177]
	s_waitcnt vmcnt(2)
	ds_read_b128 v[182:185], v231 offset:16
	ds_read_b128 v[186:189], v231 offset:0
	v_lshlrev_b32_e32 v190, 16, v244
	v_and_b32_e32 v191, 0xffff0000, v244
	v_lshlrev_b32_e32 v192, 16, v245
	v_and_b32_e32 v193, 0xffff0000, v245
	v_lshlrev_b32_e32 v194, 16, v246
	v_and_b32_e32 v195, 0xffff0000, v246
	v_lshlrev_b32_e32 v196, 16, v247
	v_and_b32_e32 v197, 0xffff0000, v247
	s_mov_b32 s100, 0x58000
	v_lshl_add_u64 v[232:233], v[234:235], 0, s[100:101]
	global_load_dwordx4 v[244:247], v[232:233], off
	s_waitcnt lgkmcnt(0)
	v_pk_fma_f32 v[46:47], v[48:49], v[188:189], v[192:193]
	v_pk_fma_f32 v[48:49], v[168:169], v[186:187], v[190:191]
	v_pk_mul_f32 v[168:169], v[42:43], v[198:199] op_sel_hi:[1,0]
	v_pk_fma_f32 v[42:43], v[44:45], v[184:185], v[196:197]
	ds_read_b128 v[184:187], v231 offset:528
	ds_read_b128 v[188:191], v231 offset:512
	v_pk_fma_f32 v[44:45], v[168:169], v[182:183], v[194:195]
	s_waitcnt lgkmcnt(0)
	v_lshlrev_b32_e32 v178, 16, v248
	v_and_b32_e32 v179, 0xffff0000, v248
	v_lshlrev_b32_e32 v168, 16, v249
	v_and_b32_e32 v169, 0xffff0000, v249
	v_lshlrev_b32_e32 v192, 16, v250
	v_and_b32_e32 v193, 0xffff0000, v250
	v_lshlrev_b32_e32 v182, 16, v251
	v_and_b32_e32 v183, 0xffff0000, v251
	global_load_dwordx4 v[248:251], v[232:233], off offset:256
	s_waitcnt lgkmcnt(0)
	v_pk_fma_f32 v[182:183], v[36:37], v[186:187], v[182:183]
	s_waitcnt lgkmcnt(0)
	v_pk_fma_f32 v[178:179], v[38:39], v[188:189], v[178:179]
	v_pk_fma_f32 v[168:169], v[40:41], v[190:191], v[168:169]
	v_mov_b32_e32 v36, v49
	v_mov_b32_e32 v37, v179
	v_pk_fma_f32 v[184:185], v[34:35], v[184:185], v[192:193]
	v_mov_b32_e32 v34, v48
	v_mov_b32_e32 v35, v178
	v_pk_mul_f32 v[36:37], v[36:37], v[36:37]
	v_mov_b32_e32 v38, v47
	v_mov_b32_e32 v39, v169
	v_pk_fma_f32 v[34:35], v[34:35], v[34:35], v[36:37]
	v_mov_b32_e32 v36, v46
	v_mov_b32_e32 v37, v168
	v_pk_mul_f32 v[38:39], v[38:39], v[38:39]
	v_mov_b32_e32 v40, v43
	v_pk_fma_f32 v[36:37], v[36:37], v[36:37], v[38:39]
	v_mov_b32_e32 v38, v45
	v_mov_b32_e32 v39, v185
	v_pk_add_f32 v[34:35], v[34:35], v[36:37]
	v_mov_b32_e32 v36, v44
	v_mov_b32_e32 v37, v184
	v_pk_mul_f32 v[38:39], v[38:39], v[38:39]
	v_mov_b32_e32 v41, v183
	v_pk_fma_f32 v[36:37], v[36:37], v[36:37], v[38:39]
	v_mov_b32_e32 v38, v42
	v_mov_b32_e32 v39, v182
	v_pk_mul_f32 v[40:41], v[40:41], v[40:41]
	v_add_u32_e32 v186, 0xa0, v146
	v_pk_fma_f32 v[38:39], v[38:39], v[38:39], v[40:41]
	v_ashrrev_i32_e32 v187, 31, v186
	v_pk_add_f32 v[36:37], v[36:37], v[38:39]
	s_nop 0
	v_pk_add_f32 v[34:35], v[34:35], v[36:37]
	s_nop 0
	v_add_f32_e32 v221, v34, v35
	v_lshlrev_b64 v[34:35], 11, v[186:187]
	v_lshl_add_u64 v[188:189], v[158:159], 0, v[34:35]
	v_mov_b64_e32 v[34:35], v[188:189]
	s_waitcnt vmcnt(2)
;     __device__ __forceinline__ void exchange(int e, float (&sv)[2][4], float (&rv)[2][4], const Unit& u, int wr, int wc, int fr, int fq, LAS unsigned char* lds, int wid, int lane) const {
;     ...
; #pragma unroll
;         for (int ai = 0; ai < 2; ++ai)
; #pragma unroll
;             for (int m = 0; m < 4; ++m) {
;                 float v = sv[ai][m];
;                 { auto t1 = __builtin_amdgcn_permlane16_swap(__float_as_uint(v), __float_as_uint(v), false, false); v = __uint_as_float(t1[0]) + __uint_as_float(t1[1]); }
;                 v = xhalf_sum(v);
;                 if (fq == 0) P[(ai * HALF + wr * 64 + m * 16 + fr) * 4 + wc] = v;
;             }
;     __device__ __forceinline__ void fused(f32x4 (&acc)[2][2][4][2], const Unit& u, int wr, int wc, int fr, int fq, LAS unsigned char* lds, int wid, int lane) const {
;     ...
;         float dep = 0.f;
; #pragma unroll
;         for (int ai = 0; ai < 2; ++ai)
; #pragma unroll
;             for (int m = 0; m < 4; ++m) {
;                 const bf16_t* hrow = hb + (size_t)(row0 + ai * HALF + m * 16) * DM + col0;
;                 asm volatile("" : "+v"(hrow) : "v"(dep));
;                 const float r1 = rv[ai][m];
;                 float q = 0.f;
; #pragma unroll
;                 for (int bj = 0; bj < 2; ++bj) {
;                     const u32x4 hv = *(const u32x4*)(hrow + bj * HALF);
;                     const f32x4 h0 = (f32x4){__uint_as_float(hv.x << 16), __uint_as_float(hv.x & 0xffff0000u), __uint_as_float(hv.y << 16), __uint_as_float(hv.y & 0xffff0000u)};
;                     const f32x4 h1 = (f32x4){__uint_as_float(hv.z << 16), __uint_as_float(hv.z & 0xffff0000u), __uint_as_float(hv.w << 16), __uint_as_float(hv.w & 0xffff0000u)};
;                     const f32x4 gg0 = *(const f32x4*)(gpost + col0 + bj * HALF), gg1 = *(const f32x4*)(gpost + col0 + bj * HALF + 4);
;                     f32x4 x0 = h0 + acc[ai][bj][m][0] * r1 * gg0, x1 = h1 + acc[ai][bj][m][1] * r1 * gg1;
;                     acc[ai][bj][m][0] = x0; acc[ai][bj][m][1] = x1;
;                     q += ((x0[0] * x0[0] + x0[1] * x0[1]) + (x0[2] * x0[2] + x0[3] * x0[3])) + ((x1[0] * x1[0] + x1[1] * x1[1]) + (x1[2] * x1[2] + x1[3] * x1[3]));
;                 }
;                 sv[ai][m] = q;
;                 dep = q;
;             }
	ds_read_b128 v[36:39], v231 offset:16
	ds_read_b128 v[192:195], v231 offset:0
	v_lshlrev_b32_e32 v40, 16, v236
	v_and_b32_e32 v41, 0xffff0000, v236
	v_lshlrev_b32_e32 v190, 16, v237
	v_and_b32_e32 v191, 0xffff0000, v237
	v_lshlrev_b32_e32 v196, 16, v238
	v_and_b32_e32 v197, 0xffff0000, v238
	v_lshlrev_b32_e32 v198, 16, v239
	v_and_b32_e32 v199, 0xffff0000, v239
	s_waitcnt lgkmcnt(0)
	v_pk_fma_f32 v[196:197], v[26:27], v[36:37], v[196:197]
	s_waitcnt lgkmcnt(0)
	v_pk_fma_f32 v[190:191], v[32:33], v[194:195], v[190:191]
	v_pk_fma_f32 v[194:195], v[28:29], v[38:39], v[198:199]
	ds_read_b128 v[26:29], v231 offset:528
	v_pk_fma_f32 v[192:193], v[30:31], v[192:193], v[40:41]
	ds_read_b128 v[30:33], v231 offset:512
	s_waitcnt lgkmcnt(0)
	v_lshlrev_b32_e32 v34, 16, v240
	v_and_b32_e32 v35, 0xffff0000, v240
	v_lshlrev_b32_e32 v36, 16, v241
	v_and_b32_e32 v37, 0xffff0000, v241
	v_lshlrev_b32_e32 v38, 16, v242
	v_and_b32_e32 v39, 0xffff0000, v242
	v_lshlrev_b32_e32 v40, 16, v243
	v_and_b32_e32 v41, 0xffff0000, v243
	s_waitcnt lgkmcnt(0)
	v_pk_fma_f32 v[202:203], v[20:21], v[28:29], v[40:41]
	s_waitcnt lgkmcnt(0)
	v_pk_fma_f32 v[200:201], v[22:23], v[30:31], v[34:35]
	v_pk_fma_f32 v[198:199], v[24:25], v[32:33], v[36:37]
	v_mov_b32_e32 v20, v193
	v_mov_b32_e32 v21, v201
	v_pk_fma_f32 v[204:205], v[18:19], v[26:27], v[38:39]
	v_mov_b32_e32 v18, v192
	v_mov_b32_e32 v19, v200
	v_pk_mul_f32 v[20:21], v[20:21], v[20:21]
	v_mov_b32_e32 v22, v191
	v_mov_b32_e32 v23, v199
	v_pk_fma_f32 v[18:19], v[18:19], v[18:19], v[20:21]
	v_mov_b32_e32 v20, v190
	v_mov_b32_e32 v21, v198
	v_pk_mul_f32 v[22:23], v[22:23], v[22:23]
	v_mov_b32_e32 v24, v195
	v_pk_fma_f32 v[20:21], v[20:21], v[20:21], v[22:23]
	v_mov_b32_e32 v22, v197
	v_mov_b32_e32 v23, v205
	v_pk_add_f32 v[18:19], v[18:19], v[20:21]
	v_mov_b32_e32 v20, v196
	v_mov_b32_e32 v21, v204
	v_pk_mul_f32 v[22:23], v[22:23], v[22:23]
	v_mov_b32_e32 v25, v203
	v_pk_fma_f32 v[20:21], v[20:21], v[20:21], v[22:23]
	v_mov_b32_e32 v22, v194
	v_mov_b32_e32 v23, v202
	v_pk_mul_f32 v[24:25], v[24:25], v[24:25]
	s_nop 0
	v_pk_fma_f32 v[22:23], v[22:23], v[22:23], v[24:25]
	s_nop 0
	v_pk_add_f32 v[20:21], v[20:21], v[22:23]
	s_nop 0
	v_pk_add_f32 v[18:19], v[18:19], v[20:21]
	s_nop 0
	v_add_f32_e32 v154, v18, v19
	v_lshlrev_b64 v[18:19], 11, v[206:207]
	v_lshl_add_u64 v[158:159], v[158:159], 0, v[18:19]
	v_mov_b64_e32 v[18:19], v[158:159]
	ds_read_b128 v[30:33], v231 offset:16
	ds_read_b128 v[34:37], v231 offset:0
	ds_read_b128 v[18:21], v231 offset:528
	ds_read_b128 v[22:25], v231 offset:512
	s_nop 0
	v_mov_b32_e32 v156, v216
	s_nop 1
	v_permlane16_swap_b32_e32 v216, v156
	v_add_f32_e32 v156, v216, v156
	v_mov_b32_e32 v157, v156
	s_nop 1
	v_permlane32_swap_b32_e32 v156, v157
	s_and_saveexec_b64 s[10:11], s[4:5]
	v_add_f32_e32 v156, v156, v157
	ds_write_b32 v212, v156
	s_or_b64 exec, exec, s[10:11]
	v_mov_b32_e32 v156, v217
	s_nop 1
	v_permlane16_swap_b32_e32 v217, v156
	v_add_f32_e32 v156, v217, v156
	v_mov_b32_e32 v157, v156
	s_nop 1
	v_permlane32_swap_b32_e32 v156, v157
	s_and_saveexec_b64 s[10:11], s[4:5]
	v_add_f32_e32 v156, v156, v157
	ds_write_b32 v212, v156 offset:256
	s_or_b64 exec, exec, s[10:11]
	v_mov_b32_e32 v156, v218
	s_nop 1
	v_permlane16_swap_b32_e32 v218, v156
	v_add_f32_e32 v156, v218, v156
	v_mov_b32_e32 v157, v156
	s_nop 1
	v_permlane32_swap_b32_e32 v156, v157
	s_and_saveexec_b64 s[10:11], s[4:5]
	v_add_f32_e32 v156, v156, v157
	ds_write_b32 v212, v156 offset:512
	s_or_b64 exec, exec, s[10:11]
	v_mov_b32_e32 v156, v219
	s_nop 1
	v_permlane16_swap_b32_e32 v219, v156
	v_add_f32_e32 v156, v219, v156
	v_mov_b32_e32 v157, v156
	s_nop 1
	v_permlane32_swap_b32_e32 v156, v157
	s_and_saveexec_b64 s[10:11], s[4:5]
	v_add_f32_e32 v156, v156, v157
	ds_write_b32 v212, v156 offset:768
	s_or_b64 exec, exec, s[10:11]
	v_mov_b32_e32 v156, v220
	s_nop 1
	v_permlane16_swap_b32_e32 v220, v156
	v_add_f32_e32 v156, v220, v156
	v_mov_b32_e32 v157, v156
	s_nop 1
	v_permlane32_swap_b32_e32 v156, v157
	s_and_saveexec_b64 s[10:11], s[4:5]
	v_add_f32_e32 v156, v156, v157
	ds_write_b32 v212, v156 offset:2048
	s_or_b64 exec, exec, s[10:11]
	v_mov_b32_e32 v156, v221
	s_nop 1
	v_permlane16_swap_b32_e32 v221, v156
	v_add_f32_e32 v156, v221, v156
	v_mov_b32_e32 v157, v156
	s_nop 1
	v_permlane32_swap_b32_e32 v156, v157
	s_and_saveexec_b64 s[10:11], s[4:5]
	v_add_f32_e32 v156, v156, v157
	ds_write_b32 v212, v156 offset:2304
	s_or_b64 exec, exec, s[10:11]
	v_mov_b32_e32 v156, v154
	s_nop 1
	v_permlane16_swap_b32_e32 v154, v156
	v_add_f32_e32 v154, v154, v156
	v_mov_b32_e32 v156, v154
	s_nop 1
	v_permlane32_swap_b32_e32 v154, v156
	s_and_saveexec_b64 s[10:11], s[4:5]
	v_add_f32_e32 v154, v154, v156
	ds_write_b32 v212, v154 offset:2560
	s_or_b64 exec, exec, s[10:11]
	v_mov_b32_e32 v154, v155
	s_waitcnt vmcnt(0) lgkmcnt(0)
;     __device__ __forceinline__ void exchange(int e, float (&sv)[2][4], float (&rv)[2][4], const Unit& u, int wr, int wc, int fr, int fq, LAS unsigned char* lds, int wid, int lane) const {
;     ...
; #pragma unroll
;         for (int ai = 0; ai < 2; ++ai)
; #pragma unroll
;             for (int m = 0; m < 4; ++m) {
;                 float v = sv[ai][m];
;                 { auto t1 = __builtin_amdgcn_permlane16_swap(__float_as_uint(v), __float_as_uint(v), false, false); v = __uint_as_float(t1[0]) + __uint_as_float(t1[1]); }
;                 v = xhalf_sum(v);
;                 if (fq == 0) P[(ai * HALF + wr * 64 + m * 16 + fr) * 4 + wc] = v;
;             }
;         asm volatile("s_waitcnt lgkmcnt(0)" ::: "memory"); __builtin_amdgcn_s_barrier(); asm volatile("" ::: "memory");
;         const int tid = wid * 64 + lane;
;         if (tid < 256) {
;     __device__ __forceinline__ void fused(f32x4 (&acc)[2][2][4][2], const Unit& u, int wr, int wc, int fr, int fq, LAS unsigned char* lds, int wid, int lane) const {
;     ...
; #pragma unroll
;             for (int m = 0; m < 4; ++m) {
;                 const bf16_t* hrow = hb + (size_t)(row0 + ai * HALF + m * 16) * DM + col0;
;                 asm volatile("" : "+v"(hrow) : "v"(dep));
;                 const float r1 = rv[ai][m];
;                 float q = 0.f;
; #pragma unroll
;                 for (int bj = 0; bj < 2; ++bj) {
;                     const u32x4 hv = *(const u32x4*)(hrow + bj * HALF);
;                     const f32x4 h0 = (f32x4){__uint_as_float(hv.x << 16), __uint_as_float(hv.x & 0xffff0000u), __uint_as_float(hv.y << 16), __uint_as_float(hv.y & 0xffff0000u)};
;                     const f32x4 h1 = (f32x4){__uint_as_float(hv.z << 16), __uint_as_float(hv.z & 0xffff0000u), __uint_as_float(hv.w << 16), __uint_as_float(hv.w & 0xffff0000u)};
;                     const f32x4 gg0 = *(const f32x4*)(gpost + col0 + bj * HALF), gg1 = *(const f32x4*)(gpost + col0 + bj * HALF + 4);
;                     f32x4 x0 = h0 + acc[ai][bj][m][0] * r1 * gg0, x1 = h1 + acc[ai][bj][m][1] * r1 * gg1;
;                     acc[ai][bj][m][0] = x0; acc[ai][bj][m][1] = x1;
;                     q += ((x0[0] * x0[0] + x0[1] * x0[1]) + (x0[2] * x0[2] + x0[3] * x0[3])) + ((x1[0] * x1[0] + x1[1] * x1[1]) + (x1[2] * x1[2] + x1[3] * x1[3]));
;                 }
;                 sv[ai][m] = q;
;                 dep = q;
;             }
	v_lshlrev_b32_e32 v156, 16, v244
	v_and_b32_e32 v157, 0xffff0000, v244
	v_lshlrev_b32_e32 v38, 16, v245
	v_and_b32_e32 v39, 0xffff0000, v245
	v_pk_mul_f32 v[16:17], v[16:17], v[154:155] op_sel_hi:[1,0]
	v_pk_mul_f32 v[218:219], v[14:15], v[154:155] op_sel_hi:[1,0]
	v_lshlrev_b32_e32 v216, 16, v246
	v_and_b32_e32 v217, 0xffff0000, v246
	v_lshlrev_b32_e32 v40, 16, v247
	v_and_b32_e32 v41, 0xffff0000, v247
	v_pk_fma_f32 v[14:15], v[16:17], v[36:37], v[38:39]
	v_pk_fma_f32 v[16:17], v[218:219], v[34:35], v[156:157]
	v_pk_mul_f32 v[12:13], v[12:13], v[154:155] op_sel_hi:[1,0]
	v_pk_mul_f32 v[34:35], v[10:11], v[154:155] op_sel_hi:[1,0]
	v_pk_fma_f32 v[10:11], v[12:13], v[32:33], v[40:41]
	v_pk_fma_f32 v[12:13], v[34:35], v[30:31], v[216:217]
	v_mul_f32_e32 v30, v17, v17
	v_mul_f32_e32 v31, v15, v15
	v_fmac_f32_e32 v30, v16, v16
	v_fmac_f32_e32 v31, v14, v14
	v_add_f32_e32 v30, v30, v31
	v_mul_f32_e32 v31, v13, v13
	v_mul_f32_e32 v32, v11, v11
	v_fmac_f32_e32 v31, v12, v12
	v_fmac_f32_e32 v32, v10, v10
	v_add_f32_e32 v31, v31, v32
	v_add_f32_e32 v36, v30, v31
	v_lshlrev_b32_e32 v30, 16, v248
	v_and_b32_e32 v31, 0xffff0000, v248
	v_lshlrev_b32_e32 v26, 16, v249
	v_and_b32_e32 v27, 0xffff0000, v249
	v_pk_mul_f32 v[8:9], v[8:9], v[154:155] op_sel_hi:[1,0]
	v_pk_mul_f32 v[34:35], v[6:7], v[154:155] op_sel_hi:[1,0]
	v_lshlrev_b32_e32 v32, 16, v250
	v_and_b32_e32 v33, 0xffff0000, v250
	v_lshlrev_b32_e32 v28, 16, v251
	v_and_b32_e32 v29, 0xffff0000, v251
	v_pk_fma_f32 v[6:7], v[8:9], v[24:25], v[26:27]
	v_pk_fma_f32 v[8:9], v[34:35], v[22:23], v[30:31]
	v_pk_mul_f32 v[4:5], v[4:5], v[154:155] op_sel_hi:[1,0]
	v_pk_mul_f32 v[22:23], v[2:3], v[154:155] op_sel_hi:[1,0]
	v_pk_fma_f32 v[2:3], v[4:5], v[20:21], v[28:29]
	v_pk_fma_f32 v[4:5], v[22:23], v[18:19], v[32:33]
	v_mul_f32_e32 v18, v9, v9
	v_mul_f32_e32 v19, v7, v7
	v_fmac_f32_e32 v18, v8, v8
	v_fmac_f32_e32 v19, v6, v6
	v_add_f32_e32 v18, v18, v19
	v_mul_f32_e32 v19, v5, v5
	v_mul_f32_e32 v20, v3, v3
	v_fmac_f32_e32 v19, v4, v4
	v_fmac_f32_e32 v20, v2, v2
	v_add_f32_e32 v19, v19, v20
	v_add_f32_e32 v18, v18, v19
	v_add_f32_e32 v18, v36, v18
	v_mov_b32_e32 v19, v18
	s_nop 1
	v_permlane16_swap_b32_e32 v18, v19
	v_add_f32_e32 v18, v18, v19
	v_mov_b32_e32 v19, v18
	s_nop 1
	v_permlane32_swap_b32_e32 v18, v19
	s_and_saveexec_b64 s[10:11], s[4:5]
	v_add_f32_e32 v18, v18, v19
	ds_write_b32 v212, v18 offset:2816
	s_or_b64 exec, exec, s[10:11]
	s_waitcnt lgkmcnt(0)
	s_barrier
	s_and_saveexec_b64 s[10:11], s[6:7]
	s_cbranch_execz .LBB0_1452
	ds_read_b128 v[18:21], v215
	s_lshl_b64 s[42:43], s[28:29], 12
	v_lshl_add_u64 v[22:23], v[140:141], 0, s[42:43]
	s_ashr_i32 s27, s26, 31
	v_lshl_add_u64 v[22:23], s[26:27], 2, v[22:23]
	s_waitcnt lgkmcnt(0)
	v_mov_b32_e32 v24, v19
	v_mov_b32_e32 v25, v20
	v_mov_b32_e32 v19, v21
	v_pk_add_f32 v[18:19], v[24:25], v[18:19]
	s_nop 0
	v_pk_add_f32 v[18:19], v[18:19], v[18:19] op_sel:[0,1] op_sel_hi:[1,0]
	global_store_dword v[22:23], v18, off sc1

;     __device__ __forceinline__ void exchange(int e, float (&sv)[2][4], float (&rv)[2][4], const Unit& u, int wr, int wc, int fr, int fq, LAS unsigned char* lds, int wid, int lane) const {
;     ...
;         if (tid < 256) {
;             const float* sl = xbuf + ((size_t)u.pm * 256 + tid) * 4;
;             const float t0 = __hip_atomic_load(sl + 0, __ATOMIC_RELAXED, __HIP_MEMORY_SCOPE_AGENT), t1 = __hip_atomic_load(sl + 1, __ATOMIC_RELAXED, __HIP_MEMORY_SCOPE_AGENT);
;             const float t2 = __hip_atomic_load(sl + 2, __ATOMIC_RELAXED, __HIP_MEMORY_SCOPE_AGENT), t3 = __hip_atomic_load(sl + 3, __ATOMIC_RELAXED, __HIP_MEMORY_SCOPE_AGENT);
;             Sx[tid] = 1.0f / sqrtf(((t0 + t1) + (t2 + t3)) * (1.0f / 1024.0f) + RMS_EPS);
;         }
;         asm volatile("s_waitcnt vmcnt(0) lgkmcnt(0)" ::: "memory"); __builtin_amdgcn_s_barrier(); asm volatile("" ::: "memory");
; #pragma unroll
;         for (int ai = 0; ai < 2; ++ai)
; #pragma unroll
;             for (int m = 0; m < 4; ++m) rv[ai][m] = Sx[ai * HALF + wr * 64 + m * 16 + fr];
;     __device__ __forceinline__ void fused(f32x4 (&acc)[2][2][4][2], const Unit& u, int wr, int wc, int fr, int fq, LAS unsigned char* lds, int wid, int lane) const {
;     ...
;         float dep = 0.f;
; #pragma unroll
;         for (int ai = 0; ai < 2; ++ai)
; #pragma unroll
;             for (int m = 0; m < 4; ++m) {
;                 const bf16_t* hrow = hb + (size_t)(row0 + ai * HALF + m * 16) * DM + col0;
;                 asm volatile("" : "+v"(hrow) : "v"(dep));
;                 const float r1 = rv[ai][m];
;                 float q = 0.f;
; #pragma unroll
;                 for (int bj = 0; bj < 2; ++bj) {
;                     const u32x4 hv = *(const u32x4*)(hrow + bj * HALF);
;                     const f32x4 h0 = (f32x4){__uint_as_float(hv.x << 16), __uint_as_float(hv.x & 0xffff0000u), __uint_as_float(hv.y << 16), __uint_as_float(hv.y & 0xffff0000u)};
;                     const f32x4 h1 = (f32x4){__uint_as_float(hv.z << 16), __uint_as_float(hv.z & 0xffff0000u), __uint_as_float(hv.w << 16), __uint_as_float(hv.w & 0xffff0000u)};
;                     const f32x4 gg0 = *(const f32x4*)(gpost + col0 + bj * HALF), gg1 = *(const f32x4*)(gpost + col0 + bj * HALF + 4);
.LBB0_1666:
	s_waitcnt vmcnt(0) lgkmcnt(0)
	s_barrier
	s_and_saveexec_b64 s[44:45], s[6:7]
	s_cbranch_execz .LBB0_1668
	s_lshl_b64 s[10:11], s[36:37], 12
	v_lshl_add_u64 v[146:147], v[138:139], 0, s[10:11]
	v_lshl_or_b32 v232, s34, 8, v222
	v_lshlrev_b32_e32 v232, 2, v232
	global_load_dword v233, v232, s[18:19]
	global_load_dword v148, v[146:147], off sc1
	global_load_dword v150, v[146:147], off offset:4 sc1
	global_load_dword v149, v[146:147], off offset:8 sc1
	global_load_dword v151, v[146:147], off offset:12 sc1
	s_mov_b32 s10, 0xf800000
	s_waitcnt vmcnt(0)
	v_pk_add_f32 v[146:147], v[148:149], v[150:151]
	s_nop 0
	v_add_f32_e32 v146, v146, v147
	v_fmamk_f32 v146, v146, 0x3a800000, v228
	v_mul_f32_e32 v147, 0x4f800000, v146
	v_cmp_gt_f32_e32 vcc, s10, v146
	s_nop 1
	v_cndmask_b32_e32 v146, v146, v147, vcc
	v_sqrt_f32_e32 v147, v146
	s_nop 0
	v_add_u32_e32 v148, -1, v147
	v_add_u32_e32 v149, 1, v147
	v_fma_f32 v150, -v148, v147, v146
	v_fma_f32 v151, -v149, v147, v146
	v_cmp_ge_f32_e64 s[10:11], 0, v150
	s_nop 1
	v_cndmask_b32_e64 v147, v147, v148, s[10:11]
	v_cmp_lt_f32_e64 s[10:11], 0, v151
	s_nop 1
	v_cndmask_b32_e64 v147, v147, v149, s[10:11]
	v_mul_f32_e32 v148, 0x37800000, v147
	v_cndmask_b32_e32 v147, v147, v148, vcc
	v_cmp_class_f32_e32 vcc, v146, v227
	s_nop 1
	v_cndmask_b32_e32 v146, v147, v146, vcc
	v_div_scale_f32 v147, s[10:11], v146, v146, 1.0
	v_rcp_f32_e32 v148, v147
	v_div_scale_f32 v149, vcc, 1.0, v146, 1.0
	v_fma_f32 v150, -v147, v148, 1.0
	v_fmac_f32_e32 v148, v150, v148
	v_mul_f32_e32 v150, v149, v148
	v_fma_f32 v151, -v147, v150, v149
	v_fmac_f32_e32 v150, v151, v148
	v_fma_f32 v147, -v147, v150, v149
	v_div_fmas_f32 v147, v147, v148, v150
	v_div_fixup_f32 v146, v147, v146, 1.0
	ds_write_b32 v190, v146
	v_mov_b32_e32 v234, 0x21400
	v_lshl_add_u32 v232, v222, 2, v234
	ds_write_b32 v232, v233
.LBB0_1668:
	s_or_b64 exec, exec, s[44:45]
	v_mov_b32_e32 v234, 0x21400
	v_lshl_add_u32 v231, v188, 2, v234
	v_lshl_add_u32 v146, s36, 8, v1
	v_lshl_or_b32 v154, s34, 8, v188
	v_ashrrev_i32_e32 v155, 31, v154
	v_ashrrev_i32_e32 v147, 31, v146
	v_lshl_add_u64 v[164:165], v[154:155], 1, s[26:27]
	v_lshlrev_b64 v[148:149], 11, v[146:147]
	v_lshl_add_u64 v[148:149], v[164:165], 0, v[148:149]
	s_waitcnt vmcnt(0) lgkmcnt(0)
	s_barrier
	v_mov_b64_e32 v[162:163], v[148:149]
	ds_read2_b32 v[160:161], v194 offset1:16
	ds_read2_b32 v[170:171], v194 offset0:32 offset1:48
	ds_read2_b32 v[174:175], v194 offset0:128 offset1:144
	ds_read2_b32 v[158:159], v194 offset0:160 offset1:176
	v_mov_b64_e32 v[234:235], v[148:149]
	s_mov_b32 s101, 0
	global_load_dwordx4 v[236:239], v[234:235], off
	global_load_dwordx4 v[240:243], v[234:235], off offset:256
	s_mov_b32 s100, 0x8000
	v_lshl_add_u64 v[232:233], v[234:235], 0, s[100:101]
	global_load_dwordx4 v[244:247], v[232:233], off
	global_load_dwordx4 v[248:251], v[232:233], off offset:256
	v_lshl_add_u64 v[156:157], v[154:155], 2, s[18:19]
	s_waitcnt lgkmcnt(0)
	v_pk_mul_f32 v[32:33], v[32:33], v[160:161] op_sel_hi:[1,0]
	v_pk_mul_f32 v[30:31], v[30:31], v[160:161] op_sel_hi:[1,0]
	v_pk_mul_f32 v[28:29], v[28:29], v[160:161] op_sel_hi:[1,0]
	v_pk_mul_f32 v[26:27], v[26:27], v[160:161] op_sel_hi:[1,0]
	v_pk_mul_f32 v[42:43], v[42:43], v[160:161] op_sel_hi:[1,0]
	v_pk_mul_f32 v[44:45], v[44:45], v[160:161] op_sel_hi:[1,0]
	v_pk_mul_f32 v[48:49], v[48:49], v[160:161] op_sel_hi:[1,0]
	v_pk_mul_f32 v[46:47], v[46:47], v[160:161] op_sel_hi:[1,0]
	v_mov_b32_e32 v196, v161
	v_pk_mul_f32 v[60:61], v[60:61], v[196:197] op_sel_hi:[1,0]
	v_pk_mul_f32 v[58:59], v[58:59], v[196:197] op_sel_hi:[1,0]
	v_pk_mul_f32 v[64:65], v[64:65], v[196:197] op_sel_hi:[1,0]
	v_pk_mul_f32 v[62:63], v[62:63], v[196:197] op_sel_hi:[1,0]
	v_pk_mul_f32 v[74:75], v[74:75], v[196:197] op_sel_hi:[1,0]
	v_pk_mul_f32 v[76:77], v[76:77], v[196:197] op_sel_hi:[1,0]
	v_pk_mul_f32 v[80:81], v[80:81], v[196:197] op_sel_hi:[1,0]
	v_pk_mul_f32 v[78:79], v[78:79], v[196:197] op_sel_hi:[1,0]
	v_pk_mul_f32 v[90:91], v[90:91], v[170:171] op_sel_hi:[1,0]
	v_pk_mul_f32 v[92:93], v[92:93], v[170:171] op_sel_hi:[1,0]
	v_pk_mul_f32 v[96:97], v[96:97], v[170:171] op_sel_hi:[1,0]
	v_pk_mul_f32 v[94:95], v[94:95], v[170:171] op_sel_hi:[1,0]
	v_pk_mul_f32 v[106:107], v[106:107], v[170:171] op_sel_hi:[1,0]
	v_pk_mul_f32 v[108:109], v[108:109], v[170:171] op_sel_hi:[1,0]
	v_pk_mul_f32 v[112:113], v[112:113], v[170:171] op_sel_hi:[1,0]
	v_pk_mul_f32 v[110:111], v[110:111], v[170:171] op_sel_hi:[1,0]
	v_mov_b32_e32 v204, v171
	v_pk_mul_f32 v[116:117], v[116:117], v[204:205] op_sel_hi:[1,0]
	v_pk_mul_f32 v[114:115], v[114:115], v[204:205] op_sel_hi:[1,0]
	v_pk_mul_f32 v[120:121], v[120:121], v[204:205] op_sel_hi:[1,0]
	v_pk_mul_f32 v[118:119], v[118:119], v[204:205] op_sel_hi:[1,0]
	v_pk_mul_f32 v[126:127], v[126:127], v[204:205] op_sel_hi:[1,0]
	v_pk_mul_f32 v[128:129], v[128:129], v[204:205] op_sel_hi:[1,0]
	v_pk_mul_f32 v[124:125], v[124:125], v[204:205] op_sel_hi:[1,0]
	v_pk_mul_f32 v[122:123], v[122:123], v[204:205] op_sel_hi:[1,0]
	v_pk_mul_f32 v[102:103], v[102:103], v[174:175] op_sel_hi:[1,0]
	v_pk_mul_f32 v[104:105], v[104:105], v[174:175] op_sel_hi:[1,0]
	v_pk_mul_f32 v[100:101], v[100:101], v[174:175] op_sel_hi:[1,0]
	v_pk_mul_f32 v[98:99], v[98:99], v[174:175] op_sel_hi:[1,0]
	v_pk_mul_f32 v[86:87], v[86:87], v[174:175] op_sel_hi:[1,0]
	v_pk_mul_f32 v[88:89], v[88:89], v[174:175] op_sel_hi:[1,0]
	v_pk_mul_f32 v[84:85], v[84:85], v[174:175] op_sel_hi:[1,0]
	v_pk_mul_f32 v[82:83], v[82:83], v[174:175] op_sel_hi:[1,0]
	v_mov_b32_e32 v174, v175
	v_pk_mul_f32 v[66:67], v[66:67], v[174:175] op_sel_hi:[1,0]
	v_pk_mul_f32 v[72:73], v[72:73], v[174:175] op_sel_hi:[1,0]
;     __device__ __forceinline__ void fused(f32x4 (&acc)[2][2][4][2], const Unit& u, int wr, int wc, int fr, int fq, LAS unsigned char* lds, int wid, int lane) const {
;     ...
;         float dep = 0.f;
; #pragma unroll
;         for (int ai = 0; ai < 2; ++ai)
; #pragma unroll
;             for (int m = 0; m < 4; ++m) {
;                 const bf16_t* hrow = hb + (size_t)(row0 + ai * HALF + m * 16) * DM + col0;
;                 asm volatile("" : "+v"(hrow) : "v"(dep));
;                 const float r1 = rv[ai][m];
;                 float q = 0.f;
; #pragma unroll
;                 for (int bj = 0; bj < 2; ++bj) {
;                     const u32x4 hv = *(const u32x4*)(hrow + bj * HALF);
;                     const f32x4 h0 = (f32x4){__uint_as_float(hv.x << 16), __uint_as_float(hv.x & 0xffff0000u), __uint_as_float(hv.y << 16), __uint_as_float(hv.y & 0xffff0000u)};
;                     const f32x4 h1 = (f32x4){__uint_as_float(hv.z << 16), __uint_as_float(hv.z & 0xffff0000u), __uint_as_float(hv.w << 16), __uint_as_float(hv.w & 0xffff0000u)};
;                     const f32x4 gg0 = *(const f32x4*)(gpost + col0 + bj * HALF), gg1 = *(const f32x4*)(gpost + col0 + bj * HALF + 4);
;                     f32x4 x0 = h0 + acc[ai][bj][m][0] * r1 * gg0, x1 = h1 + acc[ai][bj][m][1] * r1 * gg1;
;                     acc[ai][bj][m][0] = x0; acc[ai][bj][m][1] = x1;
;                     q += ((x0[0] * x0[0] + x0[1] * x0[1]) + (x0[2] * x0[2] + x0[3] * x0[3])) + ((x1[0] * x1[0] + x1[1] * x1[1]) + (x1[2] * x1[2] + x1[3] * x1[3]));
;                 }
;                 sv[ai][m] = q;
;                 dep = q;
;             }
	v_pk_mul_f32 v[70:71], v[70:71], v[174:175] op_sel_hi:[1,0]
	v_pk_mul_f32 v[68:69], v[68:69], v[174:175] op_sel_hi:[1,0]
	v_pk_mul_f32 v[54:55], v[54:55], v[174:175] op_sel_hi:[1,0]
	v_pk_mul_f32 v[56:57], v[56:57], v[174:175] op_sel_hi:[1,0]
	v_pk_mul_f32 v[50:51], v[50:51], v[174:175] op_sel_hi:[1,0]
	v_pk_mul_f32 v[52:53], v[52:53], v[174:175] op_sel_hi:[1,0]
	v_pk_mul_f32 v[38:39], v[38:39], v[158:159] op_sel_hi:[1,0]
	v_pk_mul_f32 v[40:41], v[40:41], v[158:159] op_sel_hi:[1,0]
	v_pk_mul_f32 v[36:37], v[36:37], v[158:159] op_sel_hi:[1,0]
	v_pk_mul_f32 v[34:35], v[34:35], v[158:159] op_sel_hi:[1,0]
	v_pk_mul_f32 v[22:23], v[22:23], v[158:159] op_sel_hi:[1,0]
	v_pk_mul_f32 v[24:25], v[24:25], v[158:159] op_sel_hi:[1,0]
	v_pk_mul_f32 v[20:21], v[20:21], v[158:159] op_sel_hi:[1,0]
	v_pk_mul_f32 v[18:19], v[18:19], v[158:159] op_sel_hi:[1,0]
	v_mov_b32_e32 v218, v159
	v_pk_mul_f32 v[12:13], v[12:13], v[218:219] op_sel_hi:[1,0]
	v_pk_mul_f32 v[10:11], v[10:11], v[218:219] op_sel_hi:[1,0]
	v_pk_mul_f32 v[16:17], v[16:17], v[218:219] op_sel_hi:[1,0]
	v_pk_mul_f32 v[14:15], v[14:15], v[218:219] op_sel_hi:[1,0]
	v_pk_mul_f32 v[8:9], v[8:9], v[218:219] op_sel_hi:[1,0]
	v_pk_mul_f32 v[6:7], v[6:7], v[218:219] op_sel_hi:[1,0]
	v_pk_mul_f32 v[4:5], v[4:5], v[218:219] op_sel_hi:[1,0]
	v_pk_mul_f32 v[2:3], v[2:3], v[218:219] op_sel_hi:[1,0]
	s_andn2_b64 vcc, exec, s[28:29]
	s_waitcnt vmcnt(2)
	ds_read_b128 v[150:153], v231 offset:16
	ds_read_b128 v[166:169], v231 offset:0
	v_lshlrev_b32_e32 v172, 16, v236
	v_and_b32_e32 v173, 0xffff0000, v236
	v_lshlrev_b32_e32 v176, 16, v237
	v_and_b32_e32 v177, 0xffff0000, v237
	v_lshlrev_b32_e32 v178, 16, v238
	v_and_b32_e32 v179, 0xffff0000, v238
	v_lshlrev_b32_e32 v182, 16, v239
	v_and_b32_e32 v183, 0xffff0000, v239
	s_mov_b32 s100, 0x10000
	v_lshl_add_u64 v[232:233], v[234:235], 0, s[100:101]
	global_load_dwordx4 v[236:239], v[232:233], off
	s_waitcnt lgkmcnt(0)
	v_pk_fma_f32 v[32:33], v[32:33], v[152:153], v[182:183]
	v_pk_fma_f32 v[30:31], v[30:31], v[150:151], v[178:179]
	ds_read_b128 v[150:153], v231 offset:528
	s_waitcnt lgkmcnt(0)
	v_pk_fma_f32 v[28:29], v[28:29], v[168:169], v[176:177]
	v_pk_fma_f32 v[26:27], v[26:27], v[166:167], v[172:173]
	ds_read_b128 v[166:169], v231 offset:512
	s_waitcnt lgkmcnt(0)
	v_lshlrev_b32_e32 v162, 16, v240
	v_and_b32_e32 v163, 0xffff0000, v240
	v_lshlrev_b32_e32 v172, 16, v241
	v_and_b32_e32 v173, 0xffff0000, v241
	v_lshlrev_b32_e32 v176, 16, v242
	v_and_b32_e32 v177, 0xffff0000, v242
	v_lshlrev_b32_e32 v178, 16, v243
	v_and_b32_e32 v179, 0xffff0000, v243
	global_load_dwordx4 v[240:243], v[232:233], off offset:256
	s_waitcnt lgkmcnt(0)
	v_pk_fma_f32 v[48:49], v[48:49], v[152:153], v[178:179]
	s_waitcnt lgkmcnt(0)
	v_pk_fma_f32 v[42:43], v[42:43], v[166:167], v[162:163]
	v_pk_fma_f32 v[44:45], v[44:45], v[168:169], v[172:173]
	v_mov_b32_e32 v152, v27
	v_mov_b32_e32 v153, v43
	v_pk_fma_f32 v[46:47], v[46:47], v[150:151], v[176:177]
	v_mov_b32_e32 v150, v26
	v_mov_b32_e32 v151, v42
	v_pk_mul_f32 v[152:153], v[152:153], v[152:153]
	v_mov_b32_e32 v162, v29
	v_mov_b32_e32 v163, v45
	v_pk_fma_f32 v[150:151], v[150:151], v[150:151], v[152:153]
	v_mov_b32_e32 v152, v28
	v_mov_b32_e32 v153, v44
	v_pk_mul_f32 v[162:163], v[162:163], v[162:163]
	v_mov_b32_e32 v166, v33
	v_pk_fma_f32 v[152:153], v[152:153], v[152:153], v[162:163]
	v_mov_b32_e32 v162, v31
	v_mov_b32_e32 v163, v47
	v_pk_add_f32 v[150:151], v[150:151], v[152:153]
	v_mov_b32_e32 v152, v30
	v_mov_b32_e32 v153, v46
	v_pk_mul_f32 v[162:163], v[162:163], v[162:163]
	v_mov_b32_e32 v167, v49
	v_pk_fma_f32 v[152:153], v[152:153], v[152:153], v[162:163]
	v_mov_b32_e32 v162, v32
	v_mov_b32_e32 v163, v48
	v_pk_mul_f32 v[166:167], v[166:167], v[166:167]
	s_nop 0
	v_pk_fma_f32 v[162:163], v[162:163], v[162:163], v[166:167]
	s_nop 0
	v_pk_add_f32 v[152:153], v[152:153], v[162:163]
	s_nop 0
	v_pk_add_f32 v[150:151], v[150:151], v[152:153]
	s_nop 0
	v_add_f32_e32 v195, v150, v151
	v_or_b32_e32 v150, 16, v146
	v_ashrrev_i32_e32 v151, 31, v150
	v_lshlrev_b64 v[152:153], 11, v[150:151]
	v_lshl_add_u64 v[152:153], v[164:165], 0, v[152:153]
	v_mov_b64_e32 v[162:163], v[152:153]
	s_waitcnt vmcnt(2)
	ds_read_b128 v[166:169], v231 offset:16
	ds_read_b128 v[176:179], v231 offset:0
	ds_read_b128 v[160:163], v231 offset:528
	v_lshlrev_b32_e32 v172, 16, v244
	v_and_b32_e32 v173, 0xffff0000, v244
	v_lshlrev_b32_e32 v182, 16, v245
	v_and_b32_e32 v183, 0xffff0000, v245
	v_lshlrev_b32_e32 v184, 16, v246
	v_and_b32_e32 v185, 0xffff0000, v246
	v_lshlrev_b32_e32 v186, 16, v247
	v_and_b32_e32 v187, 0xffff0000, v247
	s_mov_b32 s100, 0x18000
	v_lshl_add_u64 v[232:233], v[234:235], 0, s[100:101]
	global_load_dwordx4 v[244:247], v[232:233], off
	s_waitcnt lgkmcnt(0)
	v_pk_fma_f32 v[64:65], v[64:65], v[168:169], v[186:187]
	s_waitcnt lgkmcnt(0)
	v_pk_fma_f32 v[60:61], v[60:61], v[178:179], v[182:183]
	v_pk_fma_f32 v[58:59], v[58:59], v[176:177], v[172:173]
	v_pk_fma_f32 v[62:63], v[62:63], v[166:167], v[184:185]
	ds_read_b128 v[166:169], v231 offset:512
	s_waitcnt lgkmcnt(0)
	v_lshlrev_b32_e32 v172, 16, v248
	v_and_b32_e32 v173, 0xffff0000, v248
	v_lshlrev_b32_e32 v176, 16, v249
	v_and_b32_e32 v177, 0xffff0000, v249
	v_lshlrev_b32_e32 v178, 16, v250
	v_and_b32_e32 v179, 0xffff0000, v250
	v_lshlrev_b32_e32 v182, 16, v251
	v_and_b32_e32 v183, 0xffff0000, v251
	global_load_dwordx4 v[248:251], v[232:233], off offset:256
	s_waitcnt lgkmcnt(0)
	v_pk_fma_f32 v[80:81], v[80:81], v[162:163], v[182:183]
	s_waitcnt lgkmcnt(0)
;     __device__ __forceinline__ void fused(f32x4 (&acc)[2][2][4][2], const Unit& u, int wr, int wc, int fr, int fq, LAS unsigned char* lds, int wid, int lane) const {
;     ...
;         float dep = 0.f;
; #pragma unroll
;         for (int ai = 0; ai < 2; ++ai)
; #pragma unroll
;             for (int m = 0; m < 4; ++m) {
;                 const bf16_t* hrow = hb + (size_t)(row0 + ai * HALF + m * 16) * DM + col0;
;                 asm volatile("" : "+v"(hrow) : "v"(dep));
;                 const float r1 = rv[ai][m];
;                 float q = 0.f;
; #pragma unroll
;                 for (int bj = 0; bj < 2; ++bj) {
;                     const u32x4 hv = *(const u32x4*)(hrow + bj * HALF);
;                     const f32x4 h0 = (f32x4){__uint_as_float(hv.x << 16), __uint_as_float(hv.x & 0xffff0000u), __uint_as_float(hv.y << 16), __uint_as_float(hv.y & 0xffff0000u)};
;                     const f32x4 h1 = (f32x4){__uint_as_float(hv.z << 16), __uint_as_float(hv.z & 0xffff0000u), __uint_as_float(hv.w << 16), __uint_as_float(hv.w & 0xffff0000u)};
;                     const f32x4 gg0 = *(const f32x4*)(gpost + col0 + bj * HALF), gg1 = *(const f32x4*)(gpost + col0 + bj * HALF + 4);
;                     f32x4 x0 = h0 + acc[ai][bj][m][0] * r1 * gg0, x1 = h1 + acc[ai][bj][m][1] * r1 * gg1;
;                     acc[ai][bj][m][0] = x0; acc[ai][bj][m][1] = x1;
;                     q += ((x0[0] * x0[0] + x0[1] * x0[1]) + (x0[2] * x0[2] + x0[3] * x0[3])) + ((x1[0] * x1[0] + x1[1] * x1[1]) + (x1[2] * x1[2] + x1[3] * x1[3]));
;                 }
;                 sv[ai][m] = q;
;                 dep = q;
;             }
	v_pk_fma_f32 v[74:75], v[74:75], v[166:167], v[172:173]
	v_pk_fma_f32 v[76:77], v[76:77], v[168:169], v[176:177]
	v_mov_b32_e32 v162, v59
	v_mov_b32_e32 v163, v75
	v_pk_fma_f32 v[78:79], v[78:79], v[160:161], v[178:179]
	v_mov_b32_e32 v160, v58
	v_mov_b32_e32 v161, v74
	v_pk_mul_f32 v[162:163], v[162:163], v[162:163]
	v_mov_b32_e32 v166, v61
	v_mov_b32_e32 v167, v77
	v_pk_fma_f32 v[160:161], v[160:161], v[160:161], v[162:163]
	v_mov_b32_e32 v162, v60
	v_mov_b32_e32 v163, v76
	v_pk_mul_f32 v[166:167], v[166:167], v[166:167]
	v_mov_b32_e32 v168, v65
	v_pk_fma_f32 v[162:163], v[162:163], v[162:163], v[166:167]
	v_mov_b32_e32 v166, v63
	v_mov_b32_e32 v167, v79
	v_pk_add_f32 v[160:161], v[160:161], v[162:163]
	v_mov_b32_e32 v162, v62
	v_mov_b32_e32 v163, v78
	v_pk_mul_f32 v[166:167], v[166:167], v[166:167]
	v_mov_b32_e32 v169, v81
	v_pk_fma_f32 v[162:163], v[162:163], v[162:163], v[166:167]
	v_mov_b32_e32 v166, v64
	v_mov_b32_e32 v167, v80
	v_pk_mul_f32 v[168:169], v[168:169], v[168:169]
	s_nop 0
	v_pk_fma_f32 v[166:167], v[166:167], v[166:167], v[168:169]
	s_nop 0
	v_pk_add_f32 v[162:163], v[162:163], v[166:167]
	s_nop 0
	v_pk_add_f32 v[160:161], v[160:161], v[162:163]
	s_nop 0
	v_add_f32_e32 v196, v160, v161
	v_or_b32_e32 v160, 32, v146
	v_ashrrev_i32_e32 v161, 31, v160
	v_lshlrev_b64 v[162:163], 11, v[160:161]
	v_lshl_add_u64 v[162:163], v[164:165], 0, v[162:163]
	v_mov_b64_e32 v[166:167], v[162:163]
	s_waitcnt vmcnt(2)
	ds_read_b128 v[176:179], v231 offset:16
	ds_read_b128 v[182:185], v231 offset:0
	v_lshlrev_b32_e32 v168, 16, v236
	v_and_b32_e32 v169, 0xffff0000, v236
	v_lshlrev_b32_e32 v172, 16, v237
	v_and_b32_e32 v173, 0xffff0000, v237
	v_lshlrev_b32_e32 v186, 16, v238
	v_and_b32_e32 v187, 0xffff0000, v238
	v_lshlrev_b32_e32 v198, 16, v239
	v_and_b32_e32 v199, 0xffff0000, v239
	s_mov_b32 s100, 0x40000
	v_lshl_add_u64 v[232:233], v[234:235], 0, s[100:101]
	global_load_dwordx4 v[236:239], v[232:233], off
	s_waitcnt lgkmcnt(0)
	v_pk_fma_f32 v[96:97], v[96:97], v[178:179], v[198:199]
	s_waitcnt lgkmcnt(0)
	v_pk_fma_f32 v[90:91], v[90:91], v[182:183], v[168:169]
	ds_read_b128 v[166:169], v231 offset:528
	v_pk_fma_f32 v[92:93], v[92:93], v[184:185], v[172:173]
	v_pk_fma_f32 v[94:95], v[94:95], v[176:177], v[186:187]
	ds_read_b128 v[176:179], v231 offset:512
	s_waitcnt lgkmcnt(0)
	v_lshlrev_b32_e32 v172, 16, v240
	v_and_b32_e32 v173, 0xffff0000, v240
	v_lshlrev_b32_e32 v182, 16, v241
	v_and_b32_e32 v183, 0xffff0000, v241
	v_lshlrev_b32_e32 v184, 16, v242
	v_and_b32_e32 v185, 0xffff0000, v242
	v_lshlrev_b32_e32 v186, 16, v243
	v_and_b32_e32 v187, 0xffff0000, v243
	global_load_dwordx4 v[240:243], v[232:233], off offset:256
	s_waitcnt lgkmcnt(0)
	v_pk_fma_f32 v[112:113], v[112:113], v[168:169], v[186:187]
	s_waitcnt lgkmcnt(0)
	v_pk_fma_f32 v[106:107], v[106:107], v[176:177], v[172:173]
	v_pk_fma_f32 v[108:109], v[108:109], v[178:179], v[182:183]
	v_mov_b32_e32 v168, v91
	v_mov_b32_e32 v169, v107
	v_pk_fma_f32 v[110:111], v[110:111], v[166:167], v[184:185]
	v_mov_b32_e32 v166, v90
	v_mov_b32_e32 v167, v106
	v_pk_mul_f32 v[168:169], v[168:169], v[168:169]
	v_mov_b32_e32 v172, v93
	v_mov_b32_e32 v173, v109
	v_pk_fma_f32 v[166:167], v[166:167], v[166:167], v[168:169]
	v_mov_b32_e32 v168, v92
	v_mov_b32_e32 v169, v108
	v_pk_mul_f32 v[172:173], v[172:173], v[172:173]
	v_mov_b32_e32 v176, v97
	v_pk_fma_f32 v[168:169], v[168:169], v[168:169], v[172:173]
	v_mov_b32_e32 v172, v95
	v_mov_b32_e32 v173, v111
	v_pk_add_f32 v[166:167], v[166:167], v[168:169]
	v_mov_b32_e32 v168, v94
	v_mov_b32_e32 v169, v110
	v_pk_mul_f32 v[172:173], v[172:173], v[172:173]
	v_mov_b32_e32 v177, v113
	v_pk_fma_f32 v[168:169], v[168:169], v[168:169], v[172:173]
	v_mov_b32_e32 v172, v96
	v_mov_b32_e32 v173, v112
	v_pk_mul_f32 v[176:177], v[176:177], v[176:177]
	s_nop 0
	v_pk_fma_f32 v[172:173], v[172:173], v[172:173], v[176:177]
	s_nop 0
	v_pk_add_f32 v[168:169], v[168:169], v[172:173]
	s_nop 0
	v_pk_add_f32 v[166:167], v[166:167], v[168:169]
	s_nop 0
	v_add_f32_e32 v197, v166, v167
	v_or_b32_e32 v166, 48, v146
	v_ashrrev_i32_e32 v167, 31, v166
	v_lshlrev_b64 v[168:169], 11, v[166:167]
	v_lshl_add_u64 v[168:169], v[164:165], 0, v[168:169]
	v_mov_b64_e32 v[172:173], v[168:169]
	s_waitcnt vmcnt(2)
	ds_read_b128 v[176:179], v231 offset:16
	ds_read_b128 v[182:185], v231 offset:0
	ds_read_b128 v[170:173], v231 offset:528
	v_lshlrev_b32_e32 v186, 16, v244
	v_and_b32_e32 v187, 0xffff0000, v244
	v_lshlrev_b32_e32 v198, 16, v245
	v_and_b32_e32 v199, 0xffff0000, v245
	v_lshlrev_b32_e32 v200, 16, v246
	v_and_b32_e32 v201, 0xffff0000, v246
	v_lshlrev_b32_e32 v202, 16, v247
	v_and_b32_e32 v203, 0xffff0000, v247
	s_mov_b32 s100, 0x48000
	v_lshl_add_u64 v[232:233], v[234:235], 0, s[100:101]
	global_load_dwordx4 v[244:247], v[232:233], off
	s_waitcnt lgkmcnt(0)
	v_pk_fma_f32 v[120:121], v[120:121], v[178:179], v[202:203]
	s_waitcnt lgkmcnt(0)
	v_pk_fma_f32 v[116:117], v[116:117], v[184:185], v[198:199]
	v_pk_fma_f32 v[114:115], v[114:115], v[182:183], v[186:187]
	v_pk_fma_f32 v[118:119], v[118:119], v[176:177], v[200:201]
	ds_read_b128 v[176:179], v231 offset:512
	s_waitcnt lgkmcnt(0)
	v_lshlrev_b32_e32 v182, 16, v248
	v_and_b32_e32 v183, 0xffff0000, v248
	v_lshlrev_b32_e32 v184, 16, v249
	v_and_b32_e32 v185, 0xffff0000, v249
	v_lshlrev_b32_e32 v186, 16, v250
	v_and_b32_e32 v187, 0xffff0000, v250
	v_lshlrev_b32_e32 v198, 16, v251
	v_and_b32_e32 v199, 0xffff0000, v251
	global_load_dwordx4 v[248:251], v[232:233], off offset:256
	s_waitcnt lgkmcnt(0)
	v_pk_fma_f32 v[124:125], v[124:125], v[172:173], v[198:199]
	s_waitcnt lgkmcnt(0)
;     __device__ __forceinline__ void fused(f32x4 (&acc)[2][2][4][2], const Unit& u, int wr, int wc, int fr, int fq, LAS unsigned char* lds, int wid, int lane) const {
;     ...
;         float dep = 0.f;
; #pragma unroll
;         for (int ai = 0; ai < 2; ++ai)
; #pragma unroll
;             for (int m = 0; m < 4; ++m) {
;                 const bf16_t* hrow = hb + (size_t)(row0 + ai * HALF + m * 16) * DM + col0;
;                 asm volatile("" : "+v"(hrow) : "v"(dep));
;                 const float r1 = rv[ai][m];
;                 float q = 0.f;
; #pragma unroll
;                 for (int bj = 0; bj < 2; ++bj) {
;                     const u32x4 hv = *(const u32x4*)(hrow + bj * HALF);
;                     const f32x4 h0 = (f32x4){__uint_as_float(hv.x << 16), __uint_as_float(hv.x & 0xffff0000u), __uint_as_float(hv.y << 16), __uint_as_float(hv.y & 0xffff0000u)};
;                     const f32x4 h1 = (f32x4){__uint_as_float(hv.z << 16), __uint_as_float(hv.z & 0xffff0000u), __uint_as_float(hv.w << 16), __uint_as_float(hv.w & 0xffff0000u)};
;                     const f32x4 gg0 = *(const f32x4*)(gpost + col0 + bj * HALF), gg1 = *(const f32x4*)(gpost + col0 + bj * HALF + 4);
;                     f32x4 x0 = h0 + acc[ai][bj][m][0] * r1 * gg0, x1 = h1 + acc[ai][bj][m][1] * r1 * gg1;
;                     acc[ai][bj][m][0] = x0; acc[ai][bj][m][1] = x1;
;                     q += ((x0[0] * x0[0] + x0[1] * x0[1]) + (x0[2] * x0[2] + x0[3] * x0[3])) + ((x1[0] * x1[0] + x1[1] * x1[1]) + (x1[2] * x1[2] + x1[3] * x1[3]));
;                 }
;                 sv[ai][m] = q;
;                 dep = q;
;             }
	v_pk_fma_f32 v[126:127], v[126:127], v[176:177], v[182:183]
	v_pk_fma_f32 v[128:129], v[128:129], v[178:179], v[184:185]
	v_mov_b32_e32 v172, v115
	v_mov_b32_e32 v173, v127
	v_pk_fma_f32 v[122:123], v[122:123], v[170:171], v[186:187]
	v_mov_b32_e32 v170, v114
	v_mov_b32_e32 v171, v126
	v_pk_mul_f32 v[172:173], v[172:173], v[172:173]
	v_mov_b32_e32 v176, v117
	v_mov_b32_e32 v177, v129
	v_pk_fma_f32 v[170:171], v[170:171], v[170:171], v[172:173]
	v_mov_b32_e32 v172, v116
	v_mov_b32_e32 v173, v128
	v_pk_mul_f32 v[176:177], v[176:177], v[176:177]
	v_mov_b32_e32 v178, v121
	v_pk_fma_f32 v[172:173], v[172:173], v[172:173], v[176:177]
	v_mov_b32_e32 v176, v119
	v_mov_b32_e32 v177, v123
	v_pk_add_f32 v[170:171], v[170:171], v[172:173]
	v_mov_b32_e32 v172, v118
	v_mov_b32_e32 v173, v122
	v_pk_mul_f32 v[176:177], v[176:177], v[176:177]
	v_mov_b32_e32 v179, v125
	v_pk_fma_f32 v[172:173], v[172:173], v[172:173], v[176:177]
	v_mov_b32_e32 v176, v120
	v_mov_b32_e32 v177, v124
	v_pk_mul_f32 v[178:179], v[178:179], v[178:179]
	s_nop 0
	v_pk_fma_f32 v[176:177], v[176:177], v[176:177], v[178:179]
	s_nop 0
	v_pk_add_f32 v[172:173], v[172:173], v[176:177]
	s_nop 0
	v_pk_add_f32 v[170:171], v[170:171], v[172:173]
	s_nop 0
	v_add_f32_e32 v198, v170, v171
	v_add_u32_e32 v170, 0x80, v146
	v_ashrrev_i32_e32 v171, 31, v170
	v_lshlrev_b64 v[172:173], 11, v[170:171]
	v_lshl_add_u64 v[172:173], v[164:165], 0, v[172:173]
	v_mov_b64_e32 v[176:177], v[172:173]
	s_waitcnt vmcnt(2)
	ds_read_b128 v[182:185], v231 offset:16
	ds_read_b128 v[200:203], v231 offset:0
	v_lshlrev_b32_e32 v178, 16, v236
	v_and_b32_e32 v179, 0xffff0000, v236
	v_lshlrev_b32_e32 v186, 16, v237
	v_and_b32_e32 v187, 0xffff0000, v237
	v_lshlrev_b32_e32 v204, 16, v238
	v_and_b32_e32 v205, 0xffff0000, v238
	v_lshlrev_b32_e32 v206, 16, v239
	v_and_b32_e32 v207, 0xffff0000, v239
	s_mov_b32 s100, 0x50000
	v_lshl_add_u64 v[232:233], v[234:235], 0, s[100:101]
	global_load_dwordx4 v[236:239], v[232:233], off
	s_waitcnt lgkmcnt(0)
	v_pk_fma_f32 v[100:101], v[100:101], v[184:185], v[206:207]
	s_waitcnt lgkmcnt(0)
	v_pk_fma_f32 v[102:103], v[102:103], v[200:201], v[178:179]
	ds_read_b128 v[176:179], v231 offset:528
	v_pk_fma_f32 v[104:105], v[104:105], v[202:203], v[186:187]
	v_pk_fma_f32 v[98:99], v[98:99], v[182:183], v[204:205]
	ds_read_b128 v[182:185], v231 offset:512
	s_waitcnt lgkmcnt(0)
	v_lshlrev_b32_e32 v186, 16, v240
	v_and_b32_e32 v187, 0xffff0000, v240
	v_lshlrev_b32_e32 v200, 16, v241
	v_and_b32_e32 v201, 0xffff0000, v241
	v_lshlrev_b32_e32 v202, 16, v242
	v_and_b32_e32 v203, 0xffff0000, v242
	v_lshlrev_b32_e32 v204, 16, v243
	v_and_b32_e32 v205, 0xffff0000, v243
	global_load_dwordx4 v[240:243], v[232:233], off offset:256
	s_waitcnt lgkmcnt(0)
	v_pk_fma_f32 v[84:85], v[84:85], v[178:179], v[204:205]
	s_waitcnt lgkmcnt(0)
	v_pk_fma_f32 v[86:87], v[86:87], v[182:183], v[186:187]
	v_pk_fma_f32 v[88:89], v[88:89], v[184:185], v[200:201]
	v_mov_b32_e32 v178, v103
	v_mov_b32_e32 v179, v87
	v_pk_fma_f32 v[82:83], v[82:83], v[176:177], v[202:203]
	v_mov_b32_e32 v176, v102
	v_mov_b32_e32 v177, v86
	v_pk_mul_f32 v[178:179], v[178:179], v[178:179]
	v_mov_b32_e32 v182, v105
	v_mov_b32_e32 v183, v89
	v_pk_fma_f32 v[176:177], v[176:177], v[176:177], v[178:179]
	v_mov_b32_e32 v178, v104
	v_mov_b32_e32 v179, v88
	v_pk_mul_f32 v[182:183], v[182:183], v[182:183]
	v_mov_b32_e32 v184, v101
	v_pk_fma_f32 v[178:179], v[178:179], v[178:179], v[182:183]
	v_mov_b32_e32 v182, v99
	v_mov_b32_e32 v183, v83
	v_pk_add_f32 v[176:177], v[176:177], v[178:179]
	v_mov_b32_e32 v178, v98
	v_mov_b32_e32 v179, v82
	v_pk_mul_f32 v[182:183], v[182:183], v[182:183]
	v_mov_b32_e32 v185, v85
	v_pk_fma_f32 v[178:179], v[178:179], v[178:179], v[182:183]
	v_mov_b32_e32 v182, v100
	v_mov_b32_e32 v183, v84
	v_pk_mul_f32 v[184:185], v[184:185], v[184:185]
	s_nop 0
	v_pk_fma_f32 v[182:183], v[182:183], v[182:183], v[184:185]
	s_nop 0
	v_pk_add_f32 v[178:179], v[178:179], v[182:183]
	s_nop 0
	v_pk_add_f32 v[176:177], v[176:177], v[178:179]
	s_nop 0
	v_add_f32_e32 v199, v176, v177
	v_add_u32_e32 v176, 0x90, v146
	v_ashrrev_i32_e32 v177, 31, v176
	v_lshlrev_b64 v[178:179], 11, v[176:177]
	v_lshl_add_u64 v[178:179], v[164:165], 0, v[178:179]
	v_mov_b64_e32 v[182:183], v[178:179]
	s_waitcnt vmcnt(2)
	ds_read_b128 v[184:187], v231 offset:16
	ds_read_b128 v[200:203], v231 offset:0
	v_lshlrev_b32_e32 v204, 16, v244
	v_and_b32_e32 v205, 0xffff0000, v244
	v_lshlrev_b32_e32 v206, 16, v245
	v_and_b32_e32 v207, 0xffff0000, v245
	v_lshlrev_b32_e32 v208, 16, v246
	v_and_b32_e32 v209, 0xffff0000, v246
	v_lshlrev_b32_e32 v210, 16, v247
	v_and_b32_e32 v211, 0xffff0000, v247
	s_mov_b32 s100, 0x58000
	v_lshl_add_u64 v[232:233], v[234:235], 0, s[100:101]
	global_load_dwordx4 v[244:247], v[232:233], off
	s_waitcnt lgkmcnt(0)
	v_pk_fma_f32 v[66:67], v[66:67], v[184:185], v[208:209]
	ds_read_b128 v[182:185], v231 offset:528
	s_waitcnt lgkmcnt(0)
	v_pk_fma_f32 v[72:73], v[72:73], v[202:203], v[206:207]
	v_pk_fma_f32 v[70:71], v[70:71], v[200:201], v[204:205]
	ds_read_b128 v[200:203], v231 offset:512
	v_pk_fma_f32 v[68:69], v[68:69], v[186:187], v[210:211]
	v_mov_b32_e32 v174, v70
	s_waitcnt lgkmcnt(0)
	v_lshlrev_b32_e32 v186, 16, v248
	v_and_b32_e32 v187, 0xffff0000, v248
	v_lshlrev_b32_e32 v204, 16, v249
	v_and_b32_e32 v205, 0xffff0000, v249
	v_lshlrev_b32_e32 v206, 16, v250
	v_and_b32_e32 v207, 0xffff0000, v250
	v_lshlrev_b32_e32 v208, 16, v251
	v_and_b32_e32 v209, 0xffff0000, v251
	global_load_dwordx4 v[248:251], v[232:233], off offset:256
	s_waitcnt lgkmcnt(0)
	v_pk_fma_f32 v[50:51], v[50:51], v[182:183], v[206:207]
	s_waitcnt lgkmcnt(0)
;     __device__ __forceinline__ void fused(f32x4 (&acc)[2][2][4][2], const Unit& u, int wr, int wc, int fr, int fq, LAS unsigned char* lds, int wid, int lane) const {
;     ...
;         float dep = 0.f;
; #pragma unroll
;         for (int ai = 0; ai < 2; ++ai)
; #pragma unroll
;             for (int m = 0; m < 4; ++m) {
;                 const bf16_t* hrow = hb + (size_t)(row0 + ai * HALF + m * 16) * DM + col0;
;                 asm volatile("" : "+v"(hrow) : "v"(dep));
;                 const float r1 = rv[ai][m];
;                 float q = 0.f;
; #pragma unroll
;                 for (int bj = 0; bj < 2; ++bj) {
;                     const u32x4 hv = *(const u32x4*)(hrow + bj * HALF);
;                     const f32x4 h0 = (f32x4){__uint_as_float(hv.x << 16), __uint_as_float(hv.x & 0xffff0000u), __uint_as_float(hv.y << 16), __uint_as_float(hv.y & 0xffff0000u)};
;                     const f32x4 h1 = (f32x4){__uint_as_float(hv.z << 16), __uint_as_float(hv.z & 0xffff0000u), __uint_as_float(hv.w << 16), __uint_as_float(hv.w & 0xffff0000u)};
;                     const f32x4 gg0 = *(const f32x4*)(gpost + col0 + bj * HALF), gg1 = *(const f32x4*)(gpost + col0 + bj * HALF + 4);
;                     f32x4 x0 = h0 + acc[ai][bj][m][0] * r1 * gg0, x1 = h1 + acc[ai][bj][m][1] * r1 * gg1;
;                     acc[ai][bj][m][0] = x0; acc[ai][bj][m][1] = x1;
;                     q += ((x0[0] * x0[0] + x0[1] * x0[1]) + (x0[2] * x0[2] + x0[3] * x0[3])) + ((x1[0] * x1[0] + x1[1] * x1[1]) + (x1[2] * x1[2] + x1[3] * x1[3]));
;                 }
;                 sv[ai][m] = q;
;                 dep = q;
;             }
;         if (fout) {
	v_pk_fma_f32 v[54:55], v[54:55], v[200:201], v[186:187]
	v_pk_fma_f32 v[56:57], v[56:57], v[202:203], v[204:205]
	v_mov_b32_e32 v182, v71
	v_mov_b32_e32 v183, v55
	v_pk_fma_f32 v[52:53], v[52:53], v[184:185], v[208:209]
	v_mov_b32_e32 v175, v54
	v_pk_mul_f32 v[182:183], v[182:183], v[182:183]
	v_mov_b32_e32 v184, v73
	v_mov_b32_e32 v185, v57
	v_pk_fma_f32 v[174:175], v[174:175], v[174:175], v[182:183]
	v_mov_b32_e32 v182, v72
	v_mov_b32_e32 v183, v56
	v_pk_mul_f32 v[184:185], v[184:185], v[184:185]
	v_mov_b32_e32 v186, v69
	v_pk_fma_f32 v[182:183], v[182:183], v[182:183], v[184:185]
	v_mov_b32_e32 v184, v67
	v_mov_b32_e32 v185, v51
	v_pk_add_f32 v[174:175], v[174:175], v[182:183]
	v_mov_b32_e32 v182, v66
	v_mov_b32_e32 v183, v50
	v_pk_mul_f32 v[184:185], v[184:185], v[184:185]
	v_mov_b32_e32 v187, v53
	v_pk_fma_f32 v[182:183], v[182:183], v[182:183], v[184:185]
	v_mov_b32_e32 v184, v68
	v_mov_b32_e32 v185, v52
	v_pk_mul_f32 v[186:187], v[186:187], v[186:187]
	s_nop 0
	v_pk_fma_f32 v[184:185], v[184:185], v[184:185], v[186:187]
	s_nop 0
	v_pk_add_f32 v[182:183], v[182:183], v[184:185]
	s_nop 0
	v_pk_add_f32 v[174:175], v[174:175], v[182:183]
	s_nop 0
	v_add_f32_e32 v200, v174, v175
	v_add_u32_e32 v174, 0xa0, v146
	v_ashrrev_i32_e32 v175, 31, v174
	v_lshlrev_b64 v[182:183], 11, v[174:175]
	v_lshl_add_u64 v[182:183], v[164:165], 0, v[182:183]
	v_mov_b64_e32 v[184:185], v[182:183]
	s_waitcnt vmcnt(2)
	ds_read_b128 v[202:205], v231 offset:16
	ds_read_b128 v[206:209], v231 offset:0
	v_lshlrev_b32_e32 v186, 16, v236
	v_and_b32_e32 v187, 0xffff0000, v236
	v_lshlrev_b32_e32 v210, 16, v237
	v_and_b32_e32 v211, 0xffff0000, v237
	v_lshlrev_b32_e32 v212, 16, v238
	v_and_b32_e32 v213, 0xffff0000, v238
	v_lshlrev_b32_e32 v214, 16, v239
	v_and_b32_e32 v215, 0xffff0000, v239
	s_waitcnt lgkmcnt(0)
	v_pk_fma_f32 v[36:37], v[36:37], v[204:205], v[214:215]
	s_waitcnt lgkmcnt(0)
	v_pk_fma_f32 v[38:39], v[38:39], v[206:207], v[186:187]
	ds_read_b128 v[184:187], v231 offset:528
	v_pk_fma_f32 v[40:41], v[40:41], v[208:209], v[210:211]
	v_pk_fma_f32 v[34:35], v[34:35], v[202:203], v[212:213]
	ds_read_b128 v[202:205], v231 offset:512
	s_waitcnt lgkmcnt(0)
	v_lshlrev_b32_e32 v206, 16, v240
	v_and_b32_e32 v207, 0xffff0000, v240
	v_lshlrev_b32_e32 v208, 16, v241
	v_and_b32_e32 v209, 0xffff0000, v241
	v_lshlrev_b32_e32 v210, 16, v242
	v_and_b32_e32 v211, 0xffff0000, v242
	v_lshlrev_b32_e32 v212, 16, v243
	v_and_b32_e32 v213, 0xffff0000, v243
	s_waitcnt lgkmcnt(0)
	v_pk_fma_f32 v[20:21], v[20:21], v[186:187], v[212:213]
	s_waitcnt lgkmcnt(0)
	v_pk_fma_f32 v[22:23], v[22:23], v[202:203], v[206:207]
	v_pk_fma_f32 v[24:25], v[24:25], v[204:205], v[208:209]
	v_mov_b32_e32 v186, v39
	v_mov_b32_e32 v187, v23
	v_pk_fma_f32 v[18:19], v[18:19], v[184:185], v[210:211]
	v_mov_b32_e32 v184, v38
	v_mov_b32_e32 v185, v22
	v_pk_mul_f32 v[186:187], v[186:187], v[186:187]
	v_mov_b32_e32 v202, v41
	v_mov_b32_e32 v203, v25
	v_pk_fma_f32 v[184:185], v[184:185], v[184:185], v[186:187]
	v_mov_b32_e32 v186, v40
	v_mov_b32_e32 v187, v24
	v_pk_mul_f32 v[202:203], v[202:203], v[202:203]
	v_mov_b32_e32 v204, v37
	v_pk_fma_f32 v[186:187], v[186:187], v[186:187], v[202:203]
	v_mov_b32_e32 v202, v35
	v_mov_b32_e32 v203, v19
	v_pk_add_f32 v[184:185], v[184:185], v[186:187]
	v_mov_b32_e32 v186, v34
	v_mov_b32_e32 v187, v18
	v_pk_mul_f32 v[202:203], v[202:203], v[202:203]
	v_mov_b32_e32 v205, v21
	v_pk_fma_f32 v[186:187], v[186:187], v[186:187], v[202:203]
	v_mov_b32_e32 v202, v36
	v_mov_b32_e32 v203, v20
	v_pk_mul_f32 v[204:205], v[204:205], v[204:205]
	s_nop 0
	v_pk_fma_f32 v[202:203], v[202:203], v[202:203], v[204:205]
	s_nop 0
	v_pk_add_f32 v[186:187], v[186:187], v[202:203]
	s_nop 0
	v_pk_add_f32 v[184:185], v[184:185], v[186:187]
	s_nop 0
	v_add_f32_e32 v158, v184, v185
	v_add_u32_e32 v184, 0xb0, v146
	v_ashrrev_i32_e32 v185, 31, v184
	v_lshlrev_b64 v[186:187], 11, v[184:185]
	v_lshl_add_u64 v[164:165], v[164:165], 0, v[186:187]
	v_mov_b64_e32 v[186:187], v[164:165]
	s_waitcnt vmcnt(0) lgkmcnt(0)
	ds_read_b128 v[202:205], v231 offset:16
	ds_read_b128 v[206:209], v231 offset:0
	v_lshlrev_b32_e32 v210, 16, v244
	v_and_b32_e32 v211, 0xffff0000, v244
	v_lshlrev_b32_e32 v212, 16, v245
	v_and_b32_e32 v213, 0xffff0000, v245
	v_lshlrev_b32_e32 v214, 16, v246
	v_and_b32_e32 v215, 0xffff0000, v246
	v_lshlrev_b32_e32 v216, 16, v247
	v_and_b32_e32 v217, 0xffff0000, v247
	s_waitcnt vmcnt(0) lgkmcnt(0)
	v_pk_fma_f32 v[12:13], v[12:13], v[204:205], v[216:217]
	v_pk_fma_f32 v[10:11], v[10:11], v[202:203], v[214:215]
	s_waitcnt vmcnt(0) lgkmcnt(0)
	ds_read_b128 v[202:205], v231 offset:528
	v_pk_fma_f32 v[16:17], v[16:17], v[208:209], v[212:213]
	v_pk_fma_f32 v[14:15], v[14:15], v[206:207], v[210:211]
	ds_read_b128 v[206:209], v231 offset:512
	s_waitcnt lgkmcnt(0)
	v_lshlrev_b32_e32 v186, 16, v248
	v_and_b32_e32 v187, 0xffff0000, v248
	v_lshlrev_b32_e32 v210, 16, v249
	v_and_b32_e32 v211, 0xffff0000, v249
	v_lshlrev_b32_e32 v212, 16, v250
	v_and_b32_e32 v213, 0xffff0000, v250
	v_lshlrev_b32_e32 v214, 16, v251
	v_and_b32_e32 v215, 0xffff0000, v251
	s_waitcnt vmcnt(0) lgkmcnt(0)
	v_pk_fma_f32 v[4:5], v[4:5], v[204:205], v[214:215]
	s_waitcnt vmcnt(0) lgkmcnt(0)
	v_pk_fma_f32 v[8:9], v[8:9], v[208:209], v[210:211]
	v_pk_fma_f32 v[6:7], v[6:7], v[206:207], v[186:187]
	v_pk_fma_f32 v[2:3], v[2:3], v[202:203], v[212:213]
	s_cbranch_vccnz .LBB0_1700
;     __device__ __forceinline__ void fused(f32x4 (&acc)[2][2][4][2], const Unit& u, int wr, int wc, int fr, int fq, LAS unsigned char* lds, int wid, int lane) const {
;     ...
;         if (fout) {
; #pragma unroll
;             for (int ai = 0; ai < 2; ++ai)
; #pragma unroll
;                 for (int m = 0; m < 4; ++m) { float* orow = fout + (size_t)(row0 + ai * HALF + m * 16) * DM + col0;
; #pragma unroll
;                     for (int bj = 0; bj < 2; ++bj) { *(f32x4*)(orow + bj * HALF) = acc[ai][bj][m][0]; *(f32x4*)(orow + bj * HALF + 4) = acc[ai][bj][m][1]; } }
;             return;
	v_lshlrev_b64 v[156:157], 12, v[146:147]
	v_lshl_add_u64 v[156:157], s[14:15], 0, v[156:157]
	v_lshlrev_b64 v[154:155], 2, v[154:155]
	v_lshl_add_u64 v[156:157], v[156:157], 0, v[154:155]
	global_store_dwordx4 v[156:157], v[26:29], off
	global_store_dwordx4 v[156:157], v[30:33], off offset:16
	global_store_dwordx4 v[156:157], v[42:45], off offset:512
	global_store_dwordx4 v[156:157], v[46:49], off offset:528
	v_lshlrev_b64 v[156:157], 12, v[150:151]
	v_lshl_add_u64 v[156:157], s[14:15], 0, v[156:157]
	v_lshl_add_u64 v[156:157], v[156:157], 0, v[154:155]
	global_store_dwordx4 v[156:157], v[58:61], off
	global_store_dwordx4 v[156:157], v[62:65], off offset:16
	global_store_dwordx4 v[156:157], v[74:77], off offset:512
	global_store_dwordx4 v[156:157], v[78:81], off offset:528
	v_lshlrev_b64 v[156:157], 12, v[160:161]
	v_lshl_add_u64 v[156:157], s[14:15], 0, v[156:157]
	v_lshl_add_u64 v[156:157], v[156:157], 0, v[154:155]
	global_store_dwordx4 v[156:157], v[90:93], off
	global_store_dwordx4 v[156:157], v[94:97], off offset:16
	global_store_dwordx4 v[156:157], v[106:109], off offset:512
	global_store_dwordx4 v[156:157], v[110:113], off offset:528
	v_lshlrev_b64 v[156:157], 12, v[166:167]
	v_lshl_add_u64 v[156:157], s[14:15], 0, v[156:157]
	v_lshl_add_u64 v[156:157], v[156:157], 0, v[154:155]
	global_store_dwordx4 v[156:157], v[114:117], off
	global_store_dwordx4 v[156:157], v[118:121], off offset:16
	global_store_dwordx4 v[156:157], v[126:129], off offset:512
	global_store_dwordx4 v[156:157], v[122:125], off offset:528
	v_lshlrev_b64 v[156:157], 12, v[170:171]
	v_lshl_add_u64 v[156:157], s[14:15], 0, v[156:157]
	v_lshl_add_u64 v[156:157], v[156:157], 0, v[154:155]
	global_store_dwordx4 v[156:157], v[102:105], off
	global_store_dwordx4 v[156:157], v[98:101], off offset:16
	global_store_dwordx4 v[156:157], v[86:89], off offset:512
	global_store_dwordx4 v[156:157], v[82:85], off offset:528
	v_lshlrev_b64 v[156:157], 12, v[176:177]
	v_lshl_add_u64 v[156:157], s[14:15], 0, v[156:157]
	v_lshl_add_u64 v[156:157], v[156:157], 0, v[154:155]
	global_store_dwordx4 v[156:157], v[70:73], off
	global_store_dwordx4 v[156:157], v[66:69], off offset:16
	global_store_dwordx4 v[156:157], v[54:57], off offset:512
	global_store_dwordx4 v[156:157], v[50:53], off offset:528
	v_lshlrev_b64 v[156:157], 12, v[174:175]
	v_lshl_add_u64 v[156:157], s[14:15], 0, v[156:157]
	v_lshl_add_u64 v[156:157], v[156:157], 0, v[154:155]
	global_store_dwordx4 v[156:157], v[38:41], off
	global_store_dwordx4 v[156:157], v[34:37], off offset:16
	global_store_dwordx4 v[156:157], v[22:25], off offset:512
	global_store_dwordx4 v[156:157], v[18:21], off offset:528
	v_lshlrev_b64 v[156:157], 12, v[184:185]
	v_lshl_add_u64 v[156:157], s[14:15], 0, v[156:157]
	v_lshl_add_u64 v[154:155], v[156:157], 0, v[154:155]
	global_store_dwordx4 v[154:155], v[14:17], off
	global_store_dwordx4 v[154:155], v[10:13], off offset:16
	global_store_dwordx4 v[154:155], v[6:9], off offset:512
	global_store_dwordx4 v[154:155], v[2:5], off offset:528
	s_cbranch_execnz .LBB0_1701
